# combined micro-patches: strength-reduced MLA staging addresses, global (not flat) row-stat atomics without drains, SwiGLU next-tile row-stat preload in the epilogue, on top of peel+fill
# speedup vs baseline: 1.0128x; 1.0128x over previous
;     DI void operator()(const f32x4 (&acc)[2][2][4][2], const Unit& u, int wr, int wc, int fr, int fq) const {
;     ...
;             for (int m = 0; m < 4; ++m) {
;                 const int r = row0 + ai * HALF + m * 16;
;                 const float rs = ss ? __builtin_amdgcn_rsqf(ssv[ai][m] * inv_dim + EPS) : 1.f;
; #pragma unroll
;                 for (int bj = 0; bj < 2; ++bj) {
;                     float v[8];
; #pragma unroll
;                     for (int j = 0; j < 4; ++j) { v[j] = acc[ai][bj][m][0][j] * rs; v[4 + j] = acc[ai][bj][m][1][j] * rs; }
;                     bool do_rope = false;
;                     if (MODE == 1) {
;                         const bool cq = (u.pn == 6) || (u.pn == 7 && bj == 0), ckv = (u.pn == 7 && bj == 1);
;                         if (cq || ckv) {
;                             float q = 0.f;
; #pragma unroll
;                             for (int j = 0; j < 8; ++j) q += v[j] * v[j];
;                             q += __shfl_xor(q, 16); q += __shfl_xor(q, 32);
;                             if (fq == 0) unsafeAtomicAdd((cq ? ss_cq : ss_ckv) + r, q);
;                         }
.LBB0_448:
	v_rsq_f32_e32 v142, v145
	s_and_b32 s1, s0, -2
	v_bfe_u32 v158, v144, 4, 2
	s_cmp_eq_u32 s1, 6
	v_cndmask_b32_e64 v142, v142, 1.0, s[28:29]
	v_cmp_eq_u32_e64 s[10:11], 0, v158
	v_pk_mul_f32 v[144:145], v[126:127], v[142:143] op_sel_hi:[1,0]
	v_pk_mul_f32 v[126:127], v[122:123], v[142:143] op_sel_hi:[1,0]
	v_pk_mul_f32 v[128:129], v[128:129], v[142:143] op_sel_hi:[1,0]
	s_cselect_b64 s[48:49], -1, 0
	s_cmp_lg_u32 s1, 6
	v_pk_mul_f32 v[146:147], v[124:125], v[142:143] op_sel_hi:[1,0]
	s_cbranch_scc1 .LBB0_452
	v_pk_mul_f32 v[122:123], v[144:145], v[144:145]
	v_pk_mul_f32 v[124:125], v[128:129], v[128:129]
	v_add_f32_e32 v122, v122, v123
	v_add_f32_e32 v122, v124, v122
	v_pk_mul_f32 v[160:161], v[126:127], v[126:127]
	v_add_f32_e32 v122, v125, v122
	v_and_b32_e32 v124, 64, v243
	v_add_f32_e32 v122, v160, v122
	v_xor_b32_e32 v123, 16, v243
	v_add_u32_e32 v124, 64, v124
	v_pk_mul_f32 v[162:163], v[146:147], v[146:147]
	v_add_f32_e32 v122, v161, v122
	v_cmp_lt_i32_e32 vcc, v123, v124
	v_add_f32_e32 v122, v162, v122
	v_add_f32_e32 v122, v163, v122
	v_cndmask_b32_e32 v123, v243, v123, vcc
	v_lshlrev_b32_e32 v123, 2, v123
	ds_bpermute_b32 v123, v123, v122
	s_waitcnt lgkmcnt(0)
	v_add_f32_e32 v122, v122, v123
	v_xor_b32_e32 v123, 32, v243
	v_cmp_lt_i32_e32 vcc, v123, v124
	s_nop 1
	v_cndmask_b32_e32 v123, v243, v123, vcc
	v_lshlrev_b32_e32 v123, 2, v123
	ds_bpermute_b32 v123, v123, v122
	s_and_saveexec_b64 s[6:7], s[10:11]
	s_cbranch_execz .LBB0_451
	v_lshl_add_u64 v[124:125], v[140:141], 2, s[22:23]
	s_waitcnt lgkmcnt(0)
	v_add_f32_e32 v122, v122, v123
	global_atomic_add_f32 v[124:125], v122, off

; DI unsigned pk2(float lo, float hi) { f32x2_t v = {lo, hi}; bf16x2_t b = __builtin_convertvector(v, bf16x2_t); return __builtin_bit_cast(unsigned, b); }
;     DI void operator()(const f32x4 (&acc)[2][2][4][2], const Unit& u, int wr, int wc, int fr, int fq) const {
;     ...
;                 for (int bj = 0; bj < 2; ++bj) {
;                     float v[8];
; #pragma unroll
;                     for (int j = 0; j < 4; ++j) { v[j] = acc[ai][bj][m][0][j] * rs; v[4 + j] = acc[ai][bj][m][1][j] * rs; }
;                     bool do_rope = false;
;                     if (MODE == 1) {
;                         const bool cq = (u.pn == 6) || (u.pn == 7 && bj == 0), ckv = (u.pn == 7 && bj == 1);
;                         if (cq || ckv) {
;                             float q = 0.f;
; #pragma unroll
;                             for (int j = 0; j < 8; ++j) q += v[j] * v[j];
;                             q += __shfl_xor(q, 16); q += __shfl_xor(q, 32);
;                             if (fq == 0) unsafeAtomicAdd((cq ? ss_cq : ss_ckv) + r, q);
;                         }
;     ...
;                     u32x4 w; w.x = pk2(v[0], v[1]); w.y = pk2(v[2], v[3]); w.z = pk2(v[4], v[5]); w.w = pk2(v[6], v[7]);
;                     *(u32x4*)(O + (size_t)r * ldc + col0 + bj * HALF) = w;
.LBB0_454:
	s_lshl_b32 s1, s0, 8
	s_or_b32 s1, s1, s60
	v_lshl_or_b32 v122, v158, 3, s1
	s_cmp_eq_u32 s0, 6
	v_readlane_b32 s0, v254, 51
	v_readlane_b32 s1, v254, 52
	v_cvt_pk_bf16_f32 v160, v126, v127
	v_mov_b32_e32 v143, v142
	v_mov_b64_e32 v[124:125], s[0:1]
	v_mad_u64_u32 v[124:125], s[0:1], v140, s86, v[124:125]
	v_mov_b32_e32 v126, v125
	v_mad_u64_u32 v[126:127], s[0:1], v141, s86, v[126:127]
	s_waitcnt lgkmcnt(0)
	v_ashrrev_i32_e32 v123, 31, v122
	v_mov_b32_e32 v125, v126
	v_cndmask_b32_e64 v126, 0, 1, s[48:49]
	s_cselect_b64 s[6:7], -1, 0
	v_cvt_pk_bf16_f32 v158, v144, v145
	v_cvt_pk_bf16_f32 v159, v128, v129
	v_cvt_pk_bf16_f32 v161, v146, v147
	v_lshl_add_u64 v[124:125], v[122:123], 1, v[124:125]
	v_pk_mul_f32 v[118:119], v[118:119], v[142:143]
	v_pk_mul_f32 v[114:115], v[114:115], v[142:143]
	v_pk_mul_f32 v[120:121], v[120:121], v[142:143]
	v_cmp_ne_u32_e64 s[16:17], 1, v126
	s_andn2_b64 vcc, exec, s[48:49]
	v_pk_mul_f32 v[116:117], v[116:117], v[142:143]
	global_store_dwordx4 v[124:125], v[158:161], off
	s_cbranch_vccnz .LBB0_458
	v_pk_mul_f32 v[126:127], v[118:119], v[118:119]
	v_pk_mul_f32 v[128:129], v[120:121], v[120:121]
	v_add_f32_e32 v126, v126, v127
	v_add_f32_e32 v126, v128, v126
	v_pk_mul_f32 v[142:143], v[114:115], v[114:115]
	v_add_f32_e32 v126, v129, v126
	v_and_b32_e32 v128, 64, v243
	v_add_f32_e32 v126, v142, v126
	v_xor_b32_e32 v127, 16, v243
	v_add_u32_e32 v128, 64, v128
	v_pk_mul_f32 v[144:145], v[116:117], v[116:117]
	v_add_f32_e32 v126, v143, v126
	v_cmp_lt_i32_e32 vcc, v127, v128
	v_add_f32_e32 v126, v144, v126
	v_add_f32_e32 v126, v145, v126
	v_cndmask_b32_e32 v127, v243, v127, vcc
	v_lshlrev_b32_e32 v127, 2, v127
	ds_bpermute_b32 v127, v127, v126
	s_waitcnt lgkmcnt(0)
	v_add_f32_e32 v126, v126, v127
	v_xor_b32_e32 v127, 32, v243
	v_cmp_lt_i32_e32 vcc, v127, v128
	s_nop 1
	v_cndmask_b32_e32 v127, v243, v127, vcc
	v_lshlrev_b32_e32 v127, 2, v127
	ds_bpermute_b32 v127, v127, v126
	s_and_saveexec_b64 s[48:49], s[10:11]
	s_cbranch_execz .LBB0_457
	s_and_b64 s[0:1], s[6:7], exec
	s_cselect_b32 s0, s23, s21
	s_cselect_b32 s1, s22, s20
	v_mov_b32_e32 v128, s1
	v_mov_b32_e32 v129, s0
	v_lshl_add_u64 v[128:129], v[140:141], 2, v[128:129]
	s_waitcnt lgkmcnt(0)
	v_add_f32_e32 v126, v126, v127
	global_atomic_add_f32 v[128:129], v126, off

; DI unsigned pk2(float lo, float hi) { f32x2_t v = {lo, hi}; bf16x2_t b = __builtin_convertvector(v, bf16x2_t); return __builtin_bit_cast(unsigned, b); }
;     DI void operator()(const f32x4 (&acc)[2][2][4][2], const Unit& u, int wr, int wc, int fr, int fq) const {
;     ...
;             for (int m = 0; m < 4; ++m) {
;                 const int r = row0 + ai * HALF + m * 16;
;                 const float rs = ss ? __builtin_amdgcn_rsqf(ssv[ai][m] * inv_dim + EPS) : 1.f;
; #pragma unroll
;                 for (int bj = 0; bj < 2; ++bj) {
;                     float v[8];
; #pragma unroll
;                     for (int j = 0; j < 4; ++j) { v[j] = acc[ai][bj][m][0][j] * rs; v[4 + j] = acc[ai][bj][m][1][j] * rs; }
;                     bool do_rope = false;
;                     if (MODE == 1) {
;                         const bool cq = (u.pn == 6) || (u.pn == 7 && bj == 0), ckv = (u.pn == 7 && bj == 1);
;                         if (cq || ckv) {
;                             float q = 0.f;
; #pragma unroll
;                             for (int j = 0; j < 8; ++j) q += v[j] * v[j];
;                             q += __shfl_xor(q, 16); q += __shfl_xor(q, 32);
;                             if (fq == 0) unsafeAtomicAdd((cq ? ss_cq : ss_ckv) + r, q);
;                         }
;     ...
;                     u32x4 w; w.x = pk2(v[0], v[1]); w.y = pk2(v[2], v[3]); w.z = pk2(v[4], v[5]); w.w = pk2(v[6], v[7]);
;                     *(u32x4*)(O + (size_t)r * ldc + col0 + bj * HALF) = w;
.LBB0_458:
	v_cvt_pk_bf16_f32 v118, v118, v119
	v_cvt_pk_bf16_f32 v119, v120, v121
	v_cvt_pk_bf16_f32 v120, v114, v115
	v_rsq_f32_e32 v114, v157
	v_cvt_pk_bf16_f32 v121, v116, v117
	global_store_dwordx4 v[124:125], v[118:121], off offset:256
	v_cndmask_b32_e64 v114, v114, 1.0, s[34:35]
	v_pk_mul_f32 v[116:117], v[110:111], v[114:115] op_sel_hi:[1,0]
	v_pk_mul_f32 v[110:111], v[106:107], v[114:115] op_sel_hi:[1,0]
	v_pk_mul_f32 v[112:113], v[112:113], v[114:115] op_sel_hi:[1,0]
	s_and_b64 vcc, exec, s[16:17]
	v_pk_mul_f32 v[118:119], v[108:109], v[114:115] op_sel_hi:[1,0]
	s_cbranch_vccnz .LBB0_462
	v_pk_mul_f32 v[106:107], v[116:117], v[116:117]
	v_pk_mul_f32 v[108:109], v[112:113], v[112:113]
	v_add_f32_e32 v106, v106, v107
	v_add_f32_e32 v106, v108, v106
	v_pk_mul_f32 v[120:121], v[110:111], v[110:111]
	v_add_f32_e32 v106, v109, v106
	v_and_b32_e32 v108, 64, v243
	v_add_f32_e32 v106, v120, v106
	v_xor_b32_e32 v107, 16, v243
	v_add_u32_e32 v108, 64, v108
	v_pk_mul_f32 v[124:125], v[118:119], v[118:119]
	v_add_f32_e32 v106, v121, v106
	v_cmp_lt_i32_e32 vcc, v107, v108
	v_add_f32_e32 v106, v124, v106
	v_add_f32_e32 v106, v125, v106
	v_cndmask_b32_e32 v107, v243, v107, vcc
	v_lshlrev_b32_e32 v107, 2, v107
	ds_bpermute_b32 v107, v107, v106
	s_waitcnt lgkmcnt(0)
	v_add_f32_e32 v106, v106, v107
	v_xor_b32_e32 v107, 32, v243
	v_cmp_lt_i32_e32 vcc, v107, v108
	s_nop 1
	v_cndmask_b32_e32 v107, v243, v107, vcc
	v_lshlrev_b32_e32 v107, 2, v107
	ds_bpermute_b32 v107, v107, v106
	s_and_saveexec_b64 s[48:49], s[10:11]
	s_cbranch_execz .LBB0_461
	v_lshl_add_u64 v[108:109], v[140:141], 2, s[22:23]
	s_waitcnt lgkmcnt(0)
	v_add_f32_e32 v106, v106, v107
	global_atomic_add_f32 v[108:109], v106, off offset:64

; DI unsigned pk2(float lo, float hi) { f32x2_t v = {lo, hi}; bf16x2_t b = __builtin_convertvector(v, bf16x2_t); return __builtin_bit_cast(unsigned, b); }
;     DI void operator()(const f32x4 (&acc)[2][2][4][2], const Unit& u, int wr, int wc, int fr, int fq) const {
;     ...
;                 for (int bj = 0; bj < 2; ++bj) {
;                     float v[8];
; #pragma unroll
;                     for (int j = 0; j < 4; ++j) { v[j] = acc[ai][bj][m][0][j] * rs; v[4 + j] = acc[ai][bj][m][1][j] * rs; }
;                     bool do_rope = false;
;                     if (MODE == 1) {
;                         const bool cq = (u.pn == 6) || (u.pn == 7 && bj == 0), ckv = (u.pn == 7 && bj == 1);
;                         if (cq || ckv) {
;                             float q = 0.f;
; #pragma unroll
;                             for (int j = 0; j < 8; ++j) q += v[j] * v[j];
;                             q += __shfl_xor(q, 16); q += __shfl_xor(q, 32);
;                             if (fq == 0) unsafeAtomicAdd((cq ? ss_cq : ss_ckv) + r, q);
;                         }
;     ...
;                     u32x4 w; w.x = pk2(v[0], v[1]); w.y = pk2(v[2], v[3]); w.z = pk2(v[4], v[5]); w.w = pk2(v[6], v[7]);
;                     *(u32x4*)(O + (size_t)r * ldc + col0 + bj * HALF) = w;
.LBB0_464:
	v_readlane_b32 s0, v254, 51
	v_readlane_b32 s1, v254, 52
	v_mov_b32_e32 v115, v114
	v_cvt_pk_bf16_f32 v108, v116, v117
	s_waitcnt lgkmcnt(0)
	v_mov_b64_e32 v[106:107], s[0:1]
	v_mad_i64_i32 v[106:107], s[0:1], v120, s86, v[106:107]
	v_cvt_pk_bf16_f32 v109, v112, v113
	v_cvt_pk_bf16_f32 v110, v110, v111
	v_cvt_pk_bf16_f32 v111, v118, v119
	v_lshl_add_u64 v[106:107], v[122:123], 1, v[106:107]
	global_store_dwordx4 v[106:107], v[108:111], off
	v_pk_mul_f32 v[104:105], v[104:105], v[114:115]
	s_and_b64 vcc, exec, s[16:17]
	v_pk_mul_f32 v[108:109], v[102:103], v[114:115]
	v_pk_mul_f32 v[102:103], v[98:99], v[114:115]
	v_pk_mul_f32 v[98:99], v[100:101], v[114:115]
	s_cbranch_vccnz .LBB0_468
	v_pk_mul_f32 v[100:101], v[108:109], v[108:109]
	v_pk_mul_f32 v[110:111], v[104:105], v[104:105]
	v_add_f32_e32 v100, v100, v101
	v_add_f32_e32 v100, v110, v100
	v_pk_mul_f32 v[112:113], v[102:103], v[102:103]
	v_add_f32_e32 v100, v111, v100
	v_and_b32_e32 v110, 64, v243
	v_add_f32_e32 v100, v112, v100
	v_xor_b32_e32 v101, 16, v243
	v_add_u32_e32 v110, 64, v110
	v_pk_mul_f32 v[114:115], v[98:99], v[98:99]
	v_add_f32_e32 v100, v113, v100
	v_cmp_lt_i32_e32 vcc, v101, v110
	v_add_f32_e32 v100, v114, v100
	v_add_f32_e32 v100, v115, v100
	v_cndmask_b32_e32 v101, v243, v101, vcc
	v_lshlrev_b32_e32 v101, 2, v101
	ds_bpermute_b32 v101, v101, v100
	s_waitcnt lgkmcnt(0)
	v_add_f32_e32 v100, v100, v101
	v_xor_b32_e32 v101, 32, v243
	v_cmp_lt_i32_e32 vcc, v101, v110
	s_nop 1
	v_cndmask_b32_e32 v101, v243, v101, vcc
	v_lshlrev_b32_e32 v101, 2, v101
	ds_bpermute_b32 v101, v101, v100
	s_and_saveexec_b64 s[48:49], s[10:11]
	s_cbranch_execz .LBB0_467
	s_and_b64 s[0:1], s[6:7], exec
	s_cselect_b32 s0, s23, s21
	s_cselect_b32 s1, s22, s20
	v_mov_b32_e32 v110, s1
	v_mov_b32_e32 v111, s0
	v_lshl_add_u64 v[110:111], v[140:141], 2, v[110:111]
	s_waitcnt lgkmcnt(0)
	v_add_f32_e32 v100, v100, v101
	global_atomic_add_f32 v[110:111], v100, off offset:64

; DI unsigned pk2(float lo, float hi) { f32x2_t v = {lo, hi}; bf16x2_t b = __builtin_convertvector(v, bf16x2_t); return __builtin_bit_cast(unsigned, b); }
;     DI void operator()(const f32x4 (&acc)[2][2][4][2], const Unit& u, int wr, int wc, int fr, int fq) const {
;     ...
;             for (int m = 0; m < 4; ++m) {
;                 const int r = row0 + ai * HALF + m * 16;
;                 const float rs = ss ? __builtin_amdgcn_rsqf(ssv[ai][m] * inv_dim + EPS) : 1.f;
; #pragma unroll
;                 for (int bj = 0; bj < 2; ++bj) {
;                     float v[8];
; #pragma unroll
;                     for (int j = 0; j < 4; ++j) { v[j] = acc[ai][bj][m][0][j] * rs; v[4 + j] = acc[ai][bj][m][1][j] * rs; }
;                     bool do_rope = false;
;                     if (MODE == 1) {
;                         const bool cq = (u.pn == 6) || (u.pn == 7 && bj == 0), ckv = (u.pn == 7 && bj == 1);
;                         if (cq || ckv) {
;                             float q = 0.f;
; #pragma unroll
;                             for (int j = 0; j < 8; ++j) q += v[j] * v[j];
;                             q += __shfl_xor(q, 16); q += __shfl_xor(q, 32);
;                             if (fq == 0) unsafeAtomicAdd((cq ? ss_cq : ss_ckv) + r, q);
;                         }
;     ...
;                     u32x4 w; w.x = pk2(v[0], v[1]); w.y = pk2(v[2], v[3]); w.z = pk2(v[4], v[5]); w.w = pk2(v[6], v[7]);
;                     *(u32x4*)(O + (size_t)r * ldc + col0 + bj * HALF) = w;
.LBB0_468:
	s_waitcnt lgkmcnt(0)
	v_cvt_pk_bf16_f32 v101, v104, v105
	v_rsq_f32_e32 v104, v156
	v_cvt_pk_bf16_f32 v100, v108, v109
	v_cvt_pk_bf16_f32 v102, v102, v103
	v_cvt_pk_bf16_f32 v103, v98, v99
	global_store_dwordx4 v[106:107], v[100:103], off offset:256
	v_cndmask_b32_e64 v98, v104, 1.0, s[34:35]
	v_pk_mul_f32 v[96:97], v[96:97], v[98:99] op_sel_hi:[1,0]
	v_pk_mul_f32 v[100:101], v[94:95], v[98:99] op_sel_hi:[1,0]
	v_pk_mul_f32 v[94:95], v[90:91], v[98:99] op_sel_hi:[1,0]
	s_and_b64 vcc, exec, s[16:17]
	v_pk_mul_f32 v[102:103], v[92:93], v[98:99] op_sel_hi:[1,0]
	s_cbranch_vccnz .LBB0_472
	v_pk_mul_f32 v[90:91], v[100:101], v[100:101]
	v_pk_mul_f32 v[92:93], v[96:97], v[96:97]
	v_add_f32_e32 v90, v90, v91
	v_add_f32_e32 v90, v92, v90
	v_pk_mul_f32 v[104:105], v[94:95], v[94:95]
	v_add_f32_e32 v90, v93, v90
	v_and_b32_e32 v92, 64, v243
	v_add_f32_e32 v90, v104, v90
	v_xor_b32_e32 v91, 16, v243
	v_add_u32_e32 v92, 64, v92
	v_pk_mul_f32 v[106:107], v[102:103], v[102:103]
	v_add_f32_e32 v90, v105, v90
	v_cmp_lt_i32_e32 vcc, v91, v92
	v_add_f32_e32 v90, v106, v90
	v_add_f32_e32 v90, v107, v90
	v_cndmask_b32_e32 v91, v243, v91, vcc
	v_lshlrev_b32_e32 v91, 2, v91
	ds_bpermute_b32 v91, v91, v90
	s_waitcnt lgkmcnt(0)
	v_add_f32_e32 v90, v90, v91
	v_xor_b32_e32 v91, 32, v243
	v_cmp_lt_i32_e32 vcc, v91, v92
	s_nop 1
	v_cndmask_b32_e32 v91, v243, v91, vcc
	v_lshlrev_b32_e32 v91, 2, v91
	ds_bpermute_b32 v91, v91, v90
	s_and_saveexec_b64 s[48:49], s[10:11]
	s_cbranch_execz .LBB0_471
	v_lshl_add_u64 v[92:93], v[140:141], 2, s[22:23]
	s_waitcnt lgkmcnt(0)
	v_add_f32_e32 v90, v90, v91
	global_atomic_add_f32 v[92:93], v90, off offset:128

; DI unsigned pk2(float lo, float hi) { f32x2_t v = {lo, hi}; bf16x2_t b = __builtin_convertvector(v, bf16x2_t); return __builtin_bit_cast(unsigned, b); }
;     DI void operator()(const f32x4 (&acc)[2][2][4][2], const Unit& u, int wr, int wc, int fr, int fq) const {
;     ...
;                 for (int bj = 0; bj < 2; ++bj) {
;                     float v[8];
; #pragma unroll
;                     for (int j = 0; j < 4; ++j) { v[j] = acc[ai][bj][m][0][j] * rs; v[4 + j] = acc[ai][bj][m][1][j] * rs; }
;                     bool do_rope = false;
;                     if (MODE == 1) {
;                         const bool cq = (u.pn == 6) || (u.pn == 7 && bj == 0), ckv = (u.pn == 7 && bj == 1);
;                         if (cq || ckv) {
;                             float q = 0.f;
; #pragma unroll
;                             for (int j = 0; j < 8; ++j) q += v[j] * v[j];
;                             q += __shfl_xor(q, 16); q += __shfl_xor(q, 32);
;                             if (fq == 0) unsafeAtomicAdd((cq ? ss_cq : ss_ckv) + r, q);
;                         }
;     ...
;                     u32x4 w; w.x = pk2(v[0], v[1]); w.y = pk2(v[2], v[3]); w.z = pk2(v[4], v[5]); w.w = pk2(v[6], v[7]);
;                     *(u32x4*)(O + (size_t)r * ldc + col0 + bj * HALF) = w;
.LBB0_474:
	v_readlane_b32 s0, v254, 51
	v_readlane_b32 s1, v254, 52
	v_mov_b32_e32 v99, v98
	v_cvt_pk_bf16_f32 v92, v100, v101
	s_waitcnt lgkmcnt(0)
	v_mov_b64_e32 v[90:91], s[0:1]
	v_mad_i64_i32 v[90:91], s[0:1], v104, s86, v[90:91]
	v_cvt_pk_bf16_f32 v93, v96, v97
	v_cvt_pk_bf16_f32 v94, v94, v95
	v_cvt_pk_bf16_f32 v95, v102, v103
	v_lshl_add_u64 v[90:91], v[122:123], 1, v[90:91]
	global_store_dwordx4 v[90:91], v[92:95], off
	v_pk_mul_f32 v[88:89], v[88:89], v[98:99]
	s_and_b64 vcc, exec, s[16:17]
	v_pk_mul_f32 v[92:93], v[86:87], v[98:99]
	v_pk_mul_f32 v[86:87], v[82:83], v[98:99]
	v_pk_mul_f32 v[82:83], v[84:85], v[98:99]
	s_cbranch_vccnz .LBB0_478
	v_pk_mul_f32 v[84:85], v[92:93], v[92:93]
	v_pk_mul_f32 v[94:95], v[88:89], v[88:89]
	v_add_f32_e32 v84, v84, v85
	v_add_f32_e32 v84, v94, v84
	v_pk_mul_f32 v[96:97], v[86:87], v[86:87]
	v_add_f32_e32 v84, v95, v84
	v_and_b32_e32 v94, 64, v243
	v_add_f32_e32 v84, v96, v84
	v_xor_b32_e32 v85, 16, v243
	v_add_u32_e32 v94, 64, v94
	v_pk_mul_f32 v[98:99], v[82:83], v[82:83]
	v_add_f32_e32 v84, v97, v84
	v_cmp_lt_i32_e32 vcc, v85, v94
	v_add_f32_e32 v84, v98, v84
	v_add_f32_e32 v84, v99, v84
	v_cndmask_b32_e32 v85, v243, v85, vcc
	v_lshlrev_b32_e32 v85, 2, v85
	ds_bpermute_b32 v85, v85, v84
	s_waitcnt lgkmcnt(0)
	v_add_f32_e32 v84, v84, v85
	v_xor_b32_e32 v85, 32, v243
	v_cmp_lt_i32_e32 vcc, v85, v94
	s_nop 1
	v_cndmask_b32_e32 v85, v243, v85, vcc
	v_lshlrev_b32_e32 v85, 2, v85
	ds_bpermute_b32 v85, v85, v84
	s_and_saveexec_b64 s[48:49], s[10:11]
	s_cbranch_execz .LBB0_477
	s_and_b64 s[0:1], s[6:7], exec
	s_cselect_b32 s0, s23, s21
	s_cselect_b32 s1, s22, s20
	v_mov_b32_e32 v94, s1
	v_mov_b32_e32 v95, s0
	v_lshl_add_u64 v[94:95], v[140:141], 2, v[94:95]
	s_waitcnt lgkmcnt(0)
	v_add_f32_e32 v84, v84, v85
	global_atomic_add_f32 v[94:95], v84, off offset:128

; DI unsigned pk2(float lo, float hi) { f32x2_t v = {lo, hi}; bf16x2_t b = __builtin_convertvector(v, bf16x2_t); return __builtin_bit_cast(unsigned, b); }
;     DI void operator()(const f32x4 (&acc)[2][2][4][2], const Unit& u, int wr, int wc, int fr, int fq) const {
;     ...
;             for (int m = 0; m < 4; ++m) {
;                 const int r = row0 + ai * HALF + m * 16;
;                 const float rs = ss ? __builtin_amdgcn_rsqf(ssv[ai][m] * inv_dim + EPS) : 1.f;
; #pragma unroll
;                 for (int bj = 0; bj < 2; ++bj) {
;                     float v[8];
; #pragma unroll
;                     for (int j = 0; j < 4; ++j) { v[j] = acc[ai][bj][m][0][j] * rs; v[4 + j] = acc[ai][bj][m][1][j] * rs; }
;                     bool do_rope = false;
;                     if (MODE == 1) {
;                         const bool cq = (u.pn == 6) || (u.pn == 7 && bj == 0), ckv = (u.pn == 7 && bj == 1);
;                         if (cq || ckv) {
;                             float q = 0.f;
; #pragma unroll
;                             for (int j = 0; j < 8; ++j) q += v[j] * v[j];
;                             q += __shfl_xor(q, 16); q += __shfl_xor(q, 32);
;                             if (fq == 0) unsafeAtomicAdd((cq ? ss_cq : ss_ckv) + r, q);
;                         }
;     ...
;                     u32x4 w; w.x = pk2(v[0], v[1]); w.y = pk2(v[2], v[3]); w.z = pk2(v[4], v[5]); w.w = pk2(v[6], v[7]);
;                     *(u32x4*)(O + (size_t)r * ldc + col0 + bj * HALF) = w;
.LBB0_478:
	s_waitcnt lgkmcnt(0)
	v_cvt_pk_bf16_f32 v85, v88, v89
	v_rsq_f32_e32 v88, v155
	v_cvt_pk_bf16_f32 v84, v92, v93
	v_cvt_pk_bf16_f32 v86, v86, v87
	v_cvt_pk_bf16_f32 v87, v82, v83
	global_store_dwordx4 v[90:91], v[84:87], off offset:256
	v_cndmask_b32_e64 v82, v88, 1.0, s[34:35]
	v_pk_mul_f32 v[80:81], v[80:81], v[82:83] op_sel_hi:[1,0]
	v_pk_mul_f32 v[84:85], v[78:79], v[82:83] op_sel_hi:[1,0]
	v_pk_mul_f32 v[78:79], v[74:75], v[82:83] op_sel_hi:[1,0]
	s_and_b64 vcc, exec, s[16:17]
	v_pk_mul_f32 v[86:87], v[76:77], v[82:83] op_sel_hi:[1,0]
	s_cbranch_vccnz .LBB0_482
	v_pk_mul_f32 v[74:75], v[84:85], v[84:85]
	v_pk_mul_f32 v[76:77], v[80:81], v[80:81]
	v_add_f32_e32 v74, v74, v75
	v_add_f32_e32 v74, v76, v74
	v_pk_mul_f32 v[88:89], v[78:79], v[78:79]
	v_add_f32_e32 v74, v77, v74
	v_and_b32_e32 v76, 64, v243
	v_add_f32_e32 v74, v88, v74
	v_xor_b32_e32 v75, 16, v243
	v_add_u32_e32 v76, 64, v76
	v_pk_mul_f32 v[90:91], v[86:87], v[86:87]
	v_add_f32_e32 v74, v89, v74
	v_cmp_lt_i32_e32 vcc, v75, v76
	v_add_f32_e32 v74, v90, v74
	v_add_f32_e32 v74, v91, v74
	v_cndmask_b32_e32 v75, v243, v75, vcc
	v_lshlrev_b32_e32 v75, 2, v75
	ds_bpermute_b32 v75, v75, v74
	s_waitcnt lgkmcnt(0)
	v_add_f32_e32 v74, v74, v75
	v_xor_b32_e32 v75, 32, v243
	v_cmp_lt_i32_e32 vcc, v75, v76
	s_nop 1
	v_cndmask_b32_e32 v75, v243, v75, vcc
	v_lshlrev_b32_e32 v75, 2, v75
	ds_bpermute_b32 v75, v75, v74
	s_and_saveexec_b64 s[48:49], s[10:11]
	s_cbranch_execz .LBB0_481
	v_lshl_add_u64 v[76:77], v[140:141], 2, s[22:23]
	s_waitcnt lgkmcnt(0)
	v_add_f32_e32 v74, v74, v75
	global_atomic_add_f32 v[76:77], v74, off offset:192

; DI unsigned pk2(float lo, float hi) { f32x2_t v = {lo, hi}; bf16x2_t b = __builtin_convertvector(v, bf16x2_t); return __builtin_bit_cast(unsigned, b); }
;     DI void operator()(const f32x4 (&acc)[2][2][4][2], const Unit& u, int wr, int wc, int fr, int fq) const {
;     ...
;                 for (int bj = 0; bj < 2; ++bj) {
;                     float v[8];
; #pragma unroll
;                     for (int j = 0; j < 4; ++j) { v[j] = acc[ai][bj][m][0][j] * rs; v[4 + j] = acc[ai][bj][m][1][j] * rs; }
;                     bool do_rope = false;
;                     if (MODE == 1) {
;                         const bool cq = (u.pn == 6) || (u.pn == 7 && bj == 0), ckv = (u.pn == 7 && bj == 1);
;                         if (cq || ckv) {
;                             float q = 0.f;
; #pragma unroll
;                             for (int j = 0; j < 8; ++j) q += v[j] * v[j];
;                             q += __shfl_xor(q, 16); q += __shfl_xor(q, 32);
;                             if (fq == 0) unsafeAtomicAdd((cq ? ss_cq : ss_ckv) + r, q);
;                         }
;     ...
;                     u32x4 w; w.x = pk2(v[0], v[1]); w.y = pk2(v[2], v[3]); w.z = pk2(v[4], v[5]); w.w = pk2(v[6], v[7]);
;                     *(u32x4*)(O + (size_t)r * ldc + col0 + bj * HALF) = w;
.LBB0_484:
	v_readlane_b32 s0, v254, 51
	v_readlane_b32 s1, v254, 52
	v_mov_b32_e32 v83, v82
	v_cvt_pk_bf16_f32 v76, v84, v85
	s_waitcnt lgkmcnt(0)
	v_mov_b64_e32 v[74:75], s[0:1]
	v_mad_i64_i32 v[74:75], s[0:1], v88, s86, v[74:75]
	v_cvt_pk_bf16_f32 v77, v80, v81
	v_cvt_pk_bf16_f32 v78, v78, v79
	v_cvt_pk_bf16_f32 v79, v86, v87
	v_lshl_add_u64 v[74:75], v[122:123], 1, v[74:75]
	global_store_dwordx4 v[74:75], v[76:79], off
	v_pk_mul_f32 v[72:73], v[72:73], v[82:83]
	s_and_b64 vcc, exec, s[16:17]
	v_pk_mul_f32 v[76:77], v[70:71], v[82:83]
	v_pk_mul_f32 v[70:71], v[66:67], v[82:83]
	v_pk_mul_f32 v[66:67], v[68:69], v[82:83]
	s_cbranch_vccnz .LBB0_488
	v_pk_mul_f32 v[68:69], v[76:77], v[76:77]
	v_pk_mul_f32 v[78:79], v[72:73], v[72:73]
	v_add_f32_e32 v68, v68, v69
	v_add_f32_e32 v68, v78, v68
	v_pk_mul_f32 v[80:81], v[70:71], v[70:71]
	v_add_f32_e32 v68, v79, v68
	v_and_b32_e32 v78, 64, v243
	v_add_f32_e32 v68, v80, v68
	v_xor_b32_e32 v69, 16, v243
	v_add_u32_e32 v78, 64, v78
	v_pk_mul_f32 v[82:83], v[66:67], v[66:67]
	v_add_f32_e32 v68, v81, v68
	v_cmp_lt_i32_e32 vcc, v69, v78
	v_add_f32_e32 v68, v82, v68
	v_add_f32_e32 v68, v83, v68
	v_cndmask_b32_e32 v69, v243, v69, vcc
	v_lshlrev_b32_e32 v69, 2, v69
	ds_bpermute_b32 v69, v69, v68
	s_waitcnt lgkmcnt(0)
	v_add_f32_e32 v68, v68, v69
	v_xor_b32_e32 v69, 32, v243
	v_cmp_lt_i32_e32 vcc, v69, v78
	s_nop 1
	v_cndmask_b32_e32 v69, v243, v69, vcc
	v_lshlrev_b32_e32 v69, 2, v69
	ds_bpermute_b32 v69, v69, v68
	s_and_saveexec_b64 s[48:49], s[10:11]
	s_cbranch_execz .LBB0_487
	s_and_b64 s[0:1], s[6:7], exec
	s_cselect_b32 s0, s23, s21
	s_cselect_b32 s1, s22, s20
	v_mov_b32_e32 v78, s1
	v_mov_b32_e32 v79, s0
	v_lshl_add_u64 v[78:79], v[140:141], 2, v[78:79]
	s_waitcnt lgkmcnt(0)
	v_add_f32_e32 v68, v68, v69
	global_atomic_add_f32 v[78:79], v68, off offset:192

; DI unsigned pk2(float lo, float hi) { f32x2_t v = {lo, hi}; bf16x2_t b = __builtin_convertvector(v, bf16x2_t); return __builtin_bit_cast(unsigned, b); }
;     DI void operator()(const f32x4 (&acc)[2][2][4][2], const Unit& u, int wr, int wc, int fr, int fq) const {
;     ...
;             for (int m = 0; m < 4; ++m) {
;                 const int r = row0 + ai * HALF + m * 16;
;                 const float rs = ss ? __builtin_amdgcn_rsqf(ssv[ai][m] * inv_dim + EPS) : 1.f;
; #pragma unroll
;                 for (int bj = 0; bj < 2; ++bj) {
;                     float v[8];
; #pragma unroll
;                     for (int j = 0; j < 4; ++j) { v[j] = acc[ai][bj][m][0][j] * rs; v[4 + j] = acc[ai][bj][m][1][j] * rs; }
;                     bool do_rope = false;
;                     if (MODE == 1) {
;                         const bool cq = (u.pn == 6) || (u.pn == 7 && bj == 0), ckv = (u.pn == 7 && bj == 1);
;                         if (cq || ckv) {
;                             float q = 0.f;
; #pragma unroll
;                             for (int j = 0; j < 8; ++j) q += v[j] * v[j];
;                             q += __shfl_xor(q, 16); q += __shfl_xor(q, 32);
;                             if (fq == 0) unsafeAtomicAdd((cq ? ss_cq : ss_ckv) + r, q);
;                         }
;     ...
;                     u32x4 w; w.x = pk2(v[0], v[1]); w.y = pk2(v[2], v[3]); w.z = pk2(v[4], v[5]); w.w = pk2(v[6], v[7]);
;                     *(u32x4*)(O + (size_t)r * ldc + col0 + bj * HALF) = w;
.LBB0_488:
	s_waitcnt lgkmcnt(0)
	v_cvt_pk_bf16_f32 v69, v72, v73
	v_rsq_f32_e32 v72, v154
	v_cvt_pk_bf16_f32 v68, v76, v77
	v_cvt_pk_bf16_f32 v70, v70, v71
	v_cvt_pk_bf16_f32 v71, v66, v67
	global_store_dwordx4 v[74:75], v[68:71], off offset:256
	v_cndmask_b32_e64 v66, v72, 1.0, s[34:35]
	v_pk_mul_f32 v[64:65], v[64:65], v[66:67] op_sel_hi:[1,0]
	v_pk_mul_f32 v[68:69], v[62:63], v[66:67] op_sel_hi:[1,0]
	v_pk_mul_f32 v[62:63], v[58:59], v[66:67] op_sel_hi:[1,0]
	s_and_b64 vcc, exec, s[16:17]
	v_pk_mul_f32 v[70:71], v[60:61], v[66:67] op_sel_hi:[1,0]
	s_cbranch_vccnz .LBB0_492
	v_pk_mul_f32 v[58:59], v[68:69], v[68:69]
	v_pk_mul_f32 v[60:61], v[64:65], v[64:65]
	v_add_f32_e32 v58, v58, v59
	v_add_f32_e32 v58, v60, v58
	v_pk_mul_f32 v[72:73], v[62:63], v[62:63]
	v_add_f32_e32 v58, v61, v58
	v_and_b32_e32 v60, 64, v243
	v_add_f32_e32 v58, v72, v58
	v_xor_b32_e32 v59, 16, v243
	v_add_u32_e32 v60, 64, v60
	v_pk_mul_f32 v[74:75], v[70:71], v[70:71]
	v_add_f32_e32 v58, v73, v58
	v_cmp_lt_i32_e32 vcc, v59, v60
	v_add_f32_e32 v58, v74, v58
	v_add_f32_e32 v58, v75, v58
	v_cndmask_b32_e32 v59, v243, v59, vcc
	v_lshlrev_b32_e32 v59, 2, v59
	ds_bpermute_b32 v59, v59, v58
	s_waitcnt lgkmcnt(0)
	v_add_f32_e32 v58, v58, v59
	v_xor_b32_e32 v59, 32, v243
	v_cmp_lt_i32_e32 vcc, v59, v60
	s_nop 1
	v_cndmask_b32_e32 v59, v243, v59, vcc
	v_lshlrev_b32_e32 v59, 2, v59
	ds_bpermute_b32 v59, v59, v58
	s_and_saveexec_b64 s[48:49], s[10:11]
	s_cbranch_execz .LBB0_491
	v_lshl_add_u64 v[60:61], v[140:141], 2, s[22:23]
	s_waitcnt lgkmcnt(0)
	v_add_f32_e32 v58, v58, v59
	global_atomic_add_f32 v[60:61], v58, off offset:512

; DI unsigned pk2(float lo, float hi) { f32x2_t v = {lo, hi}; bf16x2_t b = __builtin_convertvector(v, bf16x2_t); return __builtin_bit_cast(unsigned, b); }
;     DI void operator()(const f32x4 (&acc)[2][2][4][2], const Unit& u, int wr, int wc, int fr, int fq) const {
;     ...
;                 for (int bj = 0; bj < 2; ++bj) {
;                     float v[8];
; #pragma unroll
;                     for (int j = 0; j < 4; ++j) { v[j] = acc[ai][bj][m][0][j] * rs; v[4 + j] = acc[ai][bj][m][1][j] * rs; }
;                     bool do_rope = false;
;                     if (MODE == 1) {
;                         const bool cq = (u.pn == 6) || (u.pn == 7 && bj == 0), ckv = (u.pn == 7 && bj == 1);
;                         if (cq || ckv) {
;                             float q = 0.f;
; #pragma unroll
;                             for (int j = 0; j < 8; ++j) q += v[j] * v[j];
;                             q += __shfl_xor(q, 16); q += __shfl_xor(q, 32);
;                             if (fq == 0) unsafeAtomicAdd((cq ? ss_cq : ss_ckv) + r, q);
;                         }
;     ...
;                     u32x4 w; w.x = pk2(v[0], v[1]); w.y = pk2(v[2], v[3]); w.z = pk2(v[4], v[5]); w.w = pk2(v[6], v[7]);
;                     *(u32x4*)(O + (size_t)r * ldc + col0 + bj * HALF) = w;
.LBB0_494:
	v_readlane_b32 s0, v254, 51
	v_readlane_b32 s1, v254, 52
	v_mov_b32_e32 v67, v66
	v_cvt_pk_bf16_f32 v60, v68, v69
	s_waitcnt lgkmcnt(0)
	v_mov_b64_e32 v[58:59], s[0:1]
	v_mad_i64_i32 v[58:59], s[0:1], v72, s86, v[58:59]
	v_cvt_pk_bf16_f32 v61, v64, v65
	v_cvt_pk_bf16_f32 v62, v62, v63
	v_cvt_pk_bf16_f32 v63, v70, v71
	v_lshl_add_u64 v[58:59], v[122:123], 1, v[58:59]
	global_store_dwordx4 v[58:59], v[60:63], off
	v_pk_mul_f32 v[56:57], v[56:57], v[66:67]
	s_and_b64 vcc, exec, s[16:17]
	v_pk_mul_f32 v[60:61], v[54:55], v[66:67]
	v_pk_mul_f32 v[54:55], v[50:51], v[66:67]
	v_pk_mul_f32 v[50:51], v[52:53], v[66:67]
	s_cbranch_vccnz .LBB0_498
	v_pk_mul_f32 v[52:53], v[60:61], v[60:61]
	v_pk_mul_f32 v[62:63], v[56:57], v[56:57]
	v_add_f32_e32 v52, v52, v53
	v_add_f32_e32 v52, v62, v52
	v_pk_mul_f32 v[64:65], v[54:55], v[54:55]
	v_add_f32_e32 v52, v63, v52
	v_and_b32_e32 v62, 64, v243
	v_add_f32_e32 v52, v64, v52
	v_xor_b32_e32 v53, 16, v243
	v_add_u32_e32 v62, 64, v62
	v_pk_mul_f32 v[66:67], v[50:51], v[50:51]
	v_add_f32_e32 v52, v65, v52
	v_cmp_lt_i32_e32 vcc, v53, v62
	v_add_f32_e32 v52, v66, v52
	v_add_f32_e32 v52, v67, v52
	v_cndmask_b32_e32 v53, v243, v53, vcc
	v_lshlrev_b32_e32 v53, 2, v53
	ds_bpermute_b32 v53, v53, v52
	s_waitcnt lgkmcnt(0)
	v_add_f32_e32 v52, v52, v53
	v_xor_b32_e32 v53, 32, v243
	v_cmp_lt_i32_e32 vcc, v53, v62
	s_nop 1
	v_cndmask_b32_e32 v53, v243, v53, vcc
	v_lshlrev_b32_e32 v53, 2, v53
	ds_bpermute_b32 v53, v53, v52
	s_and_saveexec_b64 s[48:49], s[10:11]
	s_cbranch_execz .LBB0_497
	s_and_b64 s[0:1], s[6:7], exec
	s_cselect_b32 s0, s23, s21
	s_cselect_b32 s1, s22, s20
	v_mov_b32_e32 v62, s1
	v_mov_b32_e32 v63, s0
	v_lshl_add_u64 v[62:63], v[140:141], 2, v[62:63]
	s_waitcnt lgkmcnt(0)
	v_add_f32_e32 v52, v52, v53
	global_atomic_add_f32 v[62:63], v52, off offset:512

; DI unsigned pk2(float lo, float hi) { f32x2_t v = {lo, hi}; bf16x2_t b = __builtin_convertvector(v, bf16x2_t); return __builtin_bit_cast(unsigned, b); }
;     DI void operator()(const f32x4 (&acc)[2][2][4][2], const Unit& u, int wr, int wc, int fr, int fq) const {
;     ...
;             for (int m = 0; m < 4; ++m) {
;                 const int r = row0 + ai * HALF + m * 16;
;                 const float rs = ss ? __builtin_amdgcn_rsqf(ssv[ai][m] * inv_dim + EPS) : 1.f;
; #pragma unroll
;                 for (int bj = 0; bj < 2; ++bj) {
;                     float v[8];
; #pragma unroll
;                     for (int j = 0; j < 4; ++j) { v[j] = acc[ai][bj][m][0][j] * rs; v[4 + j] = acc[ai][bj][m][1][j] * rs; }
;                     bool do_rope = false;
;                     if (MODE == 1) {
;                         const bool cq = (u.pn == 6) || (u.pn == 7 && bj == 0), ckv = (u.pn == 7 && bj == 1);
;                         if (cq || ckv) {
;                             float q = 0.f;
; #pragma unroll
;                             for (int j = 0; j < 8; ++j) q += v[j] * v[j];
;                             q += __shfl_xor(q, 16); q += __shfl_xor(q, 32);
;                             if (fq == 0) unsafeAtomicAdd((cq ? ss_cq : ss_ckv) + r, q);
;                         }
;     ...
;                     u32x4 w; w.x = pk2(v[0], v[1]); w.y = pk2(v[2], v[3]); w.z = pk2(v[4], v[5]); w.w = pk2(v[6], v[7]);
;                     *(u32x4*)(O + (size_t)r * ldc + col0 + bj * HALF) = w;
.LBB0_498:
	s_waitcnt lgkmcnt(0)
	v_cvt_pk_bf16_f32 v53, v56, v57
	v_rsq_f32_e32 v56, v153
	v_cvt_pk_bf16_f32 v52, v60, v61
	v_cvt_pk_bf16_f32 v54, v54, v55
	v_cvt_pk_bf16_f32 v55, v50, v51
	global_store_dwordx4 v[58:59], v[52:55], off offset:256
	v_cndmask_b32_e64 v50, v56, 1.0, s[34:35]
	v_pk_mul_f32 v[48:49], v[48:49], v[50:51] op_sel_hi:[1,0]
	v_pk_mul_f32 v[52:53], v[46:47], v[50:51] op_sel_hi:[1,0]
	v_pk_mul_f32 v[46:47], v[42:43], v[50:51] op_sel_hi:[1,0]
	s_and_b64 vcc, exec, s[16:17]
	v_pk_mul_f32 v[54:55], v[44:45], v[50:51] op_sel_hi:[1,0]
	s_cbranch_vccnz .LBB0_502
	v_pk_mul_f32 v[42:43], v[52:53], v[52:53]
	v_pk_mul_f32 v[44:45], v[48:49], v[48:49]
	v_add_f32_e32 v42, v42, v43
	v_add_f32_e32 v42, v44, v42
	v_pk_mul_f32 v[56:57], v[46:47], v[46:47]
	v_add_f32_e32 v42, v45, v42
	v_and_b32_e32 v44, 64, v243
	v_add_f32_e32 v42, v56, v42
	v_xor_b32_e32 v43, 16, v243
	v_add_u32_e32 v44, 64, v44
	v_pk_mul_f32 v[58:59], v[54:55], v[54:55]
	v_add_f32_e32 v42, v57, v42
	v_cmp_lt_i32_e32 vcc, v43, v44
	v_add_f32_e32 v42, v58, v42
	v_add_f32_e32 v42, v59, v42
	v_cndmask_b32_e32 v43, v243, v43, vcc
	v_lshlrev_b32_e32 v43, 2, v43
	ds_bpermute_b32 v43, v43, v42
	s_waitcnt lgkmcnt(0)
	v_add_f32_e32 v42, v42, v43
	v_xor_b32_e32 v43, 32, v243
	v_cmp_lt_i32_e32 vcc, v43, v44
	s_nop 1
	v_cndmask_b32_e32 v43, v243, v43, vcc
	v_lshlrev_b32_e32 v43, 2, v43
	ds_bpermute_b32 v43, v43, v42
	s_and_saveexec_b64 s[48:49], s[10:11]
	s_cbranch_execz .LBB0_501
	v_lshl_add_u64 v[44:45], v[140:141], 2, s[22:23]
	s_waitcnt lgkmcnt(0)
	v_add_f32_e32 v42, v42, v43
	global_atomic_add_f32 v[44:45], v42, off offset:576

; DI unsigned pk2(float lo, float hi) { f32x2_t v = {lo, hi}; bf16x2_t b = __builtin_convertvector(v, bf16x2_t); return __builtin_bit_cast(unsigned, b); }
;     DI void operator()(const f32x4 (&acc)[2][2][4][2], const Unit& u, int wr, int wc, int fr, int fq) const {
;     ...
;                 for (int bj = 0; bj < 2; ++bj) {
;                     float v[8];
; #pragma unroll
;                     for (int j = 0; j < 4; ++j) { v[j] = acc[ai][bj][m][0][j] * rs; v[4 + j] = acc[ai][bj][m][1][j] * rs; }
;                     bool do_rope = false;
;                     if (MODE == 1) {
;                         const bool cq = (u.pn == 6) || (u.pn == 7 && bj == 0), ckv = (u.pn == 7 && bj == 1);
;                         if (cq || ckv) {
;                             float q = 0.f;
; #pragma unroll
;                             for (int j = 0; j < 8; ++j) q += v[j] * v[j];
;                             q += __shfl_xor(q, 16); q += __shfl_xor(q, 32);
;                             if (fq == 0) unsafeAtomicAdd((cq ? ss_cq : ss_ckv) + r, q);
;                         }
;     ...
;                     u32x4 w; w.x = pk2(v[0], v[1]); w.y = pk2(v[2], v[3]); w.z = pk2(v[4], v[5]); w.w = pk2(v[6], v[7]);
;                     *(u32x4*)(O + (size_t)r * ldc + col0 + bj * HALF) = w;
.LBB0_504:
	v_readlane_b32 s0, v254, 51
	v_readlane_b32 s1, v254, 52
	v_mov_b32_e32 v51, v50
	v_cvt_pk_bf16_f32 v44, v52, v53
	s_waitcnt lgkmcnt(0)
	v_mov_b64_e32 v[42:43], s[0:1]
	v_mad_i64_i32 v[42:43], s[0:1], v56, s86, v[42:43]
	v_cvt_pk_bf16_f32 v45, v48, v49
	v_cvt_pk_bf16_f32 v46, v46, v47
	v_cvt_pk_bf16_f32 v47, v54, v55
	v_lshl_add_u64 v[42:43], v[122:123], 1, v[42:43]
	global_store_dwordx4 v[42:43], v[44:47], off
	v_pk_mul_f32 v[40:41], v[40:41], v[50:51]
	s_and_b64 vcc, exec, s[16:17]
	v_pk_mul_f32 v[44:45], v[38:39], v[50:51]
	v_pk_mul_f32 v[38:39], v[34:35], v[50:51]
	v_pk_mul_f32 v[34:35], v[36:37], v[50:51]
	s_cbranch_vccnz .LBB0_508
	v_pk_mul_f32 v[36:37], v[44:45], v[44:45]
	v_pk_mul_f32 v[46:47], v[40:41], v[40:41]
	v_add_f32_e32 v36, v36, v37
	v_add_f32_e32 v36, v46, v36
	v_pk_mul_f32 v[48:49], v[38:39], v[38:39]
	v_add_f32_e32 v36, v47, v36
	v_and_b32_e32 v46, 64, v243
	v_add_f32_e32 v36, v48, v36
	v_xor_b32_e32 v37, 16, v243
	v_add_u32_e32 v46, 64, v46
	v_pk_mul_f32 v[50:51], v[34:35], v[34:35]
	v_add_f32_e32 v36, v49, v36
	v_cmp_lt_i32_e32 vcc, v37, v46
	v_add_f32_e32 v36, v50, v36
	v_add_f32_e32 v36, v51, v36
	v_cndmask_b32_e32 v37, v243, v37, vcc
	v_lshlrev_b32_e32 v37, 2, v37
	ds_bpermute_b32 v37, v37, v36
	s_waitcnt lgkmcnt(0)
	v_add_f32_e32 v36, v36, v37
	v_xor_b32_e32 v37, 32, v243
	v_cmp_lt_i32_e32 vcc, v37, v46
	s_nop 1
	v_cndmask_b32_e32 v37, v243, v37, vcc
	v_lshlrev_b32_e32 v37, 2, v37
	ds_bpermute_b32 v37, v37, v36
	s_and_saveexec_b64 s[48:49], s[10:11]
	s_cbranch_execz .LBB0_507
	s_and_b64 s[0:1], s[6:7], exec
	s_cselect_b32 s0, s23, s21
	s_cselect_b32 s1, s22, s20
	v_mov_b32_e32 v46, s1
	v_mov_b32_e32 v47, s0
	v_lshl_add_u64 v[46:47], v[140:141], 2, v[46:47]
	s_waitcnt lgkmcnt(0)
	v_add_f32_e32 v36, v36, v37
	global_atomic_add_f32 v[46:47], v36, off offset:576

; DI unsigned pk2(float lo, float hi) { f32x2_t v = {lo, hi}; bf16x2_t b = __builtin_convertvector(v, bf16x2_t); return __builtin_bit_cast(unsigned, b); }
;     DI void operator()(const f32x4 (&acc)[2][2][4][2], const Unit& u, int wr, int wc, int fr, int fq) const {
;     ...
;             for (int m = 0; m < 4; ++m) {
;                 const int r = row0 + ai * HALF + m * 16;
;                 const float rs = ss ? __builtin_amdgcn_rsqf(ssv[ai][m] * inv_dim + EPS) : 1.f;
; #pragma unroll
;                 for (int bj = 0; bj < 2; ++bj) {
;                     float v[8];
; #pragma unroll
;                     for (int j = 0; j < 4; ++j) { v[j] = acc[ai][bj][m][0][j] * rs; v[4 + j] = acc[ai][bj][m][1][j] * rs; }
;                     bool do_rope = false;
;                     if (MODE == 1) {
;                         const bool cq = (u.pn == 6) || (u.pn == 7 && bj == 0), ckv = (u.pn == 7 && bj == 1);
;                         if (cq || ckv) {
;                             float q = 0.f;
; #pragma unroll
;                             for (int j = 0; j < 8; ++j) q += v[j] * v[j];
;                             q += __shfl_xor(q, 16); q += __shfl_xor(q, 32);
;                             if (fq == 0) unsafeAtomicAdd((cq ? ss_cq : ss_ckv) + r, q);
;                         }
;     ...
;                     u32x4 w; w.x = pk2(v[0], v[1]); w.y = pk2(v[2], v[3]); w.z = pk2(v[4], v[5]); w.w = pk2(v[6], v[7]);
;                     *(u32x4*)(O + (size_t)r * ldc + col0 + bj * HALF) = w;
.LBB0_508:
	s_waitcnt lgkmcnt(0)
	v_cvt_pk_bf16_f32 v37, v40, v41
	v_rsq_f32_e32 v40, v152
	v_cvt_pk_bf16_f32 v36, v44, v45
	v_cvt_pk_bf16_f32 v38, v38, v39
	v_cvt_pk_bf16_f32 v39, v34, v35
	global_store_dwordx4 v[42:43], v[36:39], off offset:256
	v_cndmask_b32_e64 v34, v40, 1.0, s[34:35]
	v_pk_mul_f32 v[32:33], v[32:33], v[34:35] op_sel_hi:[1,0]
	v_pk_mul_f32 v[36:37], v[30:31], v[34:35] op_sel_hi:[1,0]
	v_pk_mul_f32 v[30:31], v[26:27], v[34:35] op_sel_hi:[1,0]
	s_and_b64 vcc, exec, s[16:17]
	v_pk_mul_f32 v[38:39], v[28:29], v[34:35] op_sel_hi:[1,0]
	s_cbranch_vccnz .LBB0_512
	v_pk_mul_f32 v[26:27], v[36:37], v[36:37]
	v_pk_mul_f32 v[28:29], v[32:33], v[32:33]
	v_add_f32_e32 v26, v26, v27
	v_add_f32_e32 v26, v28, v26
	v_pk_mul_f32 v[40:41], v[30:31], v[30:31]
	v_add_f32_e32 v26, v29, v26
	v_and_b32_e32 v28, 64, v243
	v_add_f32_e32 v26, v40, v26
	v_xor_b32_e32 v27, 16, v243
	v_add_u32_e32 v28, 64, v28
	v_pk_mul_f32 v[42:43], v[38:39], v[38:39]
	v_add_f32_e32 v26, v41, v26
	v_cmp_lt_i32_e32 vcc, v27, v28
	v_add_f32_e32 v26, v42, v26
	v_add_f32_e32 v26, v43, v26
	v_cndmask_b32_e32 v27, v243, v27, vcc
	v_lshlrev_b32_e32 v27, 2, v27
	ds_bpermute_b32 v27, v27, v26
	s_waitcnt lgkmcnt(0)
	v_add_f32_e32 v26, v26, v27
	v_xor_b32_e32 v27, 32, v243
	v_cmp_lt_i32_e32 vcc, v27, v28
	s_nop 1
	v_cndmask_b32_e32 v27, v243, v27, vcc
	v_lshlrev_b32_e32 v27, 2, v27
	ds_bpermute_b32 v27, v27, v26
	s_and_saveexec_b64 s[48:49], s[10:11]
	s_cbranch_execz .LBB0_511
	v_lshl_add_u64 v[28:29], v[140:141], 2, s[22:23]
	s_waitcnt lgkmcnt(0)
	v_add_f32_e32 v26, v26, v27
	global_atomic_add_f32 v[28:29], v26, off offset:640

; DI unsigned pk2(float lo, float hi) { f32x2_t v = {lo, hi}; bf16x2_t b = __builtin_convertvector(v, bf16x2_t); return __builtin_bit_cast(unsigned, b); }
;     DI void operator()(const f32x4 (&acc)[2][2][4][2], const Unit& u, int wr, int wc, int fr, int fq) const {
;     ...
;                 for (int bj = 0; bj < 2; ++bj) {
;                     float v[8];
; #pragma unroll
;                     for (int j = 0; j < 4; ++j) { v[j] = acc[ai][bj][m][0][j] * rs; v[4 + j] = acc[ai][bj][m][1][j] * rs; }
;                     bool do_rope = false;
;                     if (MODE == 1) {
;                         const bool cq = (u.pn == 6) || (u.pn == 7 && bj == 0), ckv = (u.pn == 7 && bj == 1);
;                         if (cq || ckv) {
;                             float q = 0.f;
; #pragma unroll
;                             for (int j = 0; j < 8; ++j) q += v[j] * v[j];
;                             q += __shfl_xor(q, 16); q += __shfl_xor(q, 32);
;                             if (fq == 0) unsafeAtomicAdd((cq ? ss_cq : ss_ckv) + r, q);
;                         }
;     ...
;                     u32x4 w; w.x = pk2(v[0], v[1]); w.y = pk2(v[2], v[3]); w.z = pk2(v[4], v[5]); w.w = pk2(v[6], v[7]);
;                     *(u32x4*)(O + (size_t)r * ldc + col0 + bj * HALF) = w;
.LBB0_514:
	v_readlane_b32 s0, v254, 51
	v_readlane_b32 s1, v254, 52
	v_mov_b32_e32 v35, v34
	v_cvt_pk_bf16_f32 v28, v36, v37
	s_waitcnt lgkmcnt(0)
	v_mov_b64_e32 v[26:27], s[0:1]
	v_mad_i64_i32 v[26:27], s[0:1], v40, s86, v[26:27]
	v_cvt_pk_bf16_f32 v29, v32, v33
	v_cvt_pk_bf16_f32 v30, v30, v31
	v_cvt_pk_bf16_f32 v31, v38, v39
	v_lshl_add_u64 v[26:27], v[122:123], 1, v[26:27]
	global_store_dwordx4 v[26:27], v[28:31], off
	v_pk_mul_f32 v[24:25], v[24:25], v[34:35]
	s_and_b64 vcc, exec, s[16:17]
	v_pk_mul_f32 v[28:29], v[22:23], v[34:35]
	v_pk_mul_f32 v[22:23], v[18:19], v[34:35]
	v_pk_mul_f32 v[18:19], v[20:21], v[34:35]
	s_cbranch_vccnz .LBB0_518
	v_pk_mul_f32 v[20:21], v[28:29], v[28:29]
	v_pk_mul_f32 v[30:31], v[24:25], v[24:25]
	v_add_f32_e32 v20, v20, v21
	v_add_f32_e32 v20, v30, v20
	v_pk_mul_f32 v[32:33], v[22:23], v[22:23]
	v_add_f32_e32 v20, v31, v20
	v_and_b32_e32 v30, 64, v243
	v_add_f32_e32 v20, v32, v20
	v_xor_b32_e32 v21, 16, v243
	v_add_u32_e32 v30, 64, v30
	v_pk_mul_f32 v[34:35], v[18:19], v[18:19]
	v_add_f32_e32 v20, v33, v20
	v_cmp_lt_i32_e32 vcc, v21, v30
	v_add_f32_e32 v20, v34, v20
	v_add_f32_e32 v20, v35, v20
	v_cndmask_b32_e32 v21, v243, v21, vcc
	v_lshlrev_b32_e32 v21, 2, v21
	ds_bpermute_b32 v21, v21, v20
	s_waitcnt lgkmcnt(0)
	v_add_f32_e32 v20, v20, v21
	v_xor_b32_e32 v21, 32, v243
	v_cmp_lt_i32_e32 vcc, v21, v30
	s_nop 1
	v_cndmask_b32_e32 v21, v243, v21, vcc
	v_lshlrev_b32_e32 v21, 2, v21
	ds_bpermute_b32 v21, v21, v20
	s_and_saveexec_b64 s[48:49], s[10:11]
	s_cbranch_execz .LBB0_517
	s_and_b64 s[0:1], s[6:7], exec
	s_cselect_b32 s0, s23, s21
	s_cselect_b32 s1, s22, s20
	v_mov_b32_e32 v30, s1
	v_mov_b32_e32 v31, s0
	v_lshl_add_u64 v[30:31], v[140:141], 2, v[30:31]
	s_waitcnt lgkmcnt(0)
	v_add_f32_e32 v20, v20, v21
	global_atomic_add_f32 v[30:31], v20, off offset:640

; DI unsigned pk2(float lo, float hi) { f32x2_t v = {lo, hi}; bf16x2_t b = __builtin_convertvector(v, bf16x2_t); return __builtin_bit_cast(unsigned, b); }
;     DI void operator()(const f32x4 (&acc)[2][2][4][2], const Unit& u, int wr, int wc, int fr, int fq) const {
;     ...
;             for (int m = 0; m < 4; ++m) {
;                 const int r = row0 + ai * HALF + m * 16;
;                 const float rs = ss ? __builtin_amdgcn_rsqf(ssv[ai][m] * inv_dim + EPS) : 1.f;
; #pragma unroll
;                 for (int bj = 0; bj < 2; ++bj) {
;                     float v[8];
; #pragma unroll
;                     for (int j = 0; j < 4; ++j) { v[j] = acc[ai][bj][m][0][j] * rs; v[4 + j] = acc[ai][bj][m][1][j] * rs; }
;                     bool do_rope = false;
;                     if (MODE == 1) {
;                         const bool cq = (u.pn == 6) || (u.pn == 7 && bj == 0), ckv = (u.pn == 7 && bj == 1);
;                         if (cq || ckv) {
;                             float q = 0.f;
; #pragma unroll
;                             for (int j = 0; j < 8; ++j) q += v[j] * v[j];
;                             q += __shfl_xor(q, 16); q += __shfl_xor(q, 32);
;                             if (fq == 0) unsafeAtomicAdd((cq ? ss_cq : ss_ckv) + r, q);
;                         }
;     ...
;                     u32x4 w; w.x = pk2(v[0], v[1]); w.y = pk2(v[2], v[3]); w.z = pk2(v[4], v[5]); w.w = pk2(v[6], v[7]);
;                     *(u32x4*)(O + (size_t)r * ldc + col0 + bj * HALF) = w;
.LBB0_518:
	s_waitcnt lgkmcnt(0)
	v_cvt_pk_bf16_f32 v21, v24, v25
	v_rsq_f32_e32 v24, v150
	v_cvt_pk_bf16_f32 v20, v28, v29
	v_cvt_pk_bf16_f32 v22, v22, v23
	v_cvt_pk_bf16_f32 v23, v18, v19
	global_store_dwordx4 v[26:27], v[20:23], off offset:256
	v_cndmask_b32_e64 v18, v24, 1.0, s[34:35]
	v_pk_mul_f32 v[16:17], v[16:17], v[18:19] op_sel_hi:[1,0]
	v_pk_mul_f32 v[20:21], v[14:15], v[18:19] op_sel_hi:[1,0]
	v_pk_mul_f32 v[14:15], v[10:11], v[18:19] op_sel_hi:[1,0]
	s_and_b64 vcc, exec, s[16:17]
	v_pk_mul_f32 v[22:23], v[12:13], v[18:19] op_sel_hi:[1,0]
	s_cbranch_vccnz .LBB0_522
	v_pk_mul_f32 v[10:11], v[20:21], v[20:21]
	v_pk_mul_f32 v[12:13], v[16:17], v[16:17]
	v_add_f32_e32 v10, v10, v11
	v_add_f32_e32 v10, v12, v10
	v_pk_mul_f32 v[24:25], v[14:15], v[14:15]
	v_add_f32_e32 v10, v13, v10
	v_and_b32_e32 v12, 64, v243
	v_add_f32_e32 v10, v24, v10
	v_xor_b32_e32 v11, 16, v243
	v_add_u32_e32 v12, 64, v12
	v_pk_mul_f32 v[26:27], v[22:23], v[22:23]
	v_add_f32_e32 v10, v25, v10
	v_cmp_lt_i32_e32 vcc, v11, v12
	v_add_f32_e32 v10, v26, v10
	v_add_f32_e32 v10, v27, v10
	v_cndmask_b32_e32 v11, v243, v11, vcc
	v_lshlrev_b32_e32 v11, 2, v11
	ds_bpermute_b32 v11, v11, v10
	s_waitcnt lgkmcnt(0)
	v_add_f32_e32 v10, v10, v11
	v_xor_b32_e32 v11, 32, v243
	v_cmp_lt_i32_e32 vcc, v11, v12
	s_nop 1
	v_cndmask_b32_e32 v11, v243, v11, vcc
	v_lshlrev_b32_e32 v11, 2, v11
	ds_bpermute_b32 v11, v11, v10
	s_and_saveexec_b64 s[48:49], s[10:11]
	s_cbranch_execz .LBB0_521
	v_lshl_add_u64 v[12:13], v[140:141], 2, s[22:23]
	s_waitcnt lgkmcnt(0)
	v_add_f32_e32 v10, v10, v11
	global_atomic_add_f32 v[12:13], v10, off offset:704

; DI unsigned pk2(float lo, float hi) { f32x2_t v = {lo, hi}; bf16x2_t b = __builtin_convertvector(v, bf16x2_t); return __builtin_bit_cast(unsigned, b); }
;     DI void operator()(const f32x4 (&acc)[2][2][4][2], const Unit& u, int wr, int wc, int fr, int fq) const {
;     ...
;                 for (int bj = 0; bj < 2; ++bj) {
;                     float v[8];
; #pragma unroll
;                     for (int j = 0; j < 4; ++j) { v[j] = acc[ai][bj][m][0][j] * rs; v[4 + j] = acc[ai][bj][m][1][j] * rs; }
;                     bool do_rope = false;
;                     if (MODE == 1) {
;                         const bool cq = (u.pn == 6) || (u.pn == 7 && bj == 0), ckv = (u.pn == 7 && bj == 1);
;                         if (cq || ckv) {
;                             float q = 0.f;
; #pragma unroll
;                             for (int j = 0; j < 8; ++j) q += v[j] * v[j];
;                             q += __shfl_xor(q, 16); q += __shfl_xor(q, 32);
;                             if (fq == 0) unsafeAtomicAdd((cq ? ss_cq : ss_ckv) + r, q);
;                         }
;     ...
;                     u32x4 w; w.x = pk2(v[0], v[1]); w.y = pk2(v[2], v[3]); w.z = pk2(v[4], v[5]); w.w = pk2(v[6], v[7]);
;                     *(u32x4*)(O + (size_t)r * ldc + col0 + bj * HALF) = w;
.LBB0_524:
	v_readlane_b32 s0, v254, 51
	v_readlane_b32 s1, v254, 52
	v_mov_b32_e32 v19, v18
	v_cvt_pk_bf16_f32 v12, v20, v21
	s_waitcnt lgkmcnt(0)
	v_mov_b64_e32 v[10:11], s[0:1]
	v_mad_i64_i32 v[10:11], s[0:1], v24, s86, v[10:11]
	v_cvt_pk_bf16_f32 v13, v16, v17
	v_cvt_pk_bf16_f32 v14, v14, v15
	v_cvt_pk_bf16_f32 v15, v22, v23
	v_lshl_add_u64 v[10:11], v[122:123], 1, v[10:11]
	v_pk_mul_f32 v[6:7], v[6:7], v[18:19]
	v_pk_mul_f32 v[2:3], v[2:3], v[18:19]
	v_pk_mul_f32 v[8:9], v[8:9], v[18:19]
	s_and_b64 vcc, exec, s[16:17]
	v_pk_mul_f32 v[4:5], v[4:5], v[18:19]
	global_store_dwordx4 v[10:11], v[12:15], off
	s_cbranch_vccnz .LBB0_528
	s_nop 0
	v_pk_mul_f32 v[12:13], v[6:7], v[6:7]
	v_pk_mul_f32 v[14:15], v[8:9], v[8:9]
	v_add_f32_e32 v12, v12, v13
	v_add_f32_e32 v12, v14, v12
	v_pk_mul_f32 v[16:17], v[2:3], v[2:3]
	v_add_f32_e32 v12, v15, v12
	v_and_b32_e32 v14, 64, v243
	v_add_f32_e32 v12, v16, v12
	v_xor_b32_e32 v13, 16, v243
	v_add_u32_e32 v14, 64, v14
	v_pk_mul_f32 v[18:19], v[4:5], v[4:5]
	v_add_f32_e32 v12, v17, v12
	v_cmp_lt_i32_e32 vcc, v13, v14
	v_add_f32_e32 v12, v18, v12
	v_add_f32_e32 v12, v19, v12
	v_cndmask_b32_e32 v13, v243, v13, vcc
	v_lshlrev_b32_e32 v13, 2, v13
	ds_bpermute_b32 v13, v13, v12
	s_waitcnt lgkmcnt(0)
	v_add_f32_e32 v12, v12, v13
	v_xor_b32_e32 v13, 32, v243
	v_cmp_lt_i32_e32 vcc, v13, v14
	s_nop 1
	v_cndmask_b32_e32 v13, v243, v13, vcc
	v_lshlrev_b32_e32 v13, 2, v13
	ds_bpermute_b32 v13, v13, v12
	s_and_saveexec_b64 s[12:13], s[10:11]
	s_cbranch_execz .LBB0_527
	s_and_b64 s[0:1], s[6:7], exec
	s_cselect_b32 s0, s23, s21
	s_cselect_b32 s1, s22, s20
	v_mov_b32_e32 v14, s1
	v_mov_b32_e32 v15, s0
	v_lshl_add_u64 v[14:15], v[140:141], 2, v[14:15]
	s_waitcnt lgkmcnt(0)
	v_add_f32_e32 v12, v12, v13
	global_atomic_add_f32 v[14:15], v12, off offset:704

; #define PG8_STAGE(bufoff, gbase, voff) do { _Pragma("unroll") for (int _i = 0; _i < 2; ++_i) \
;         __builtin_amdgcn_global_load_lds((const unsigned*)((const char*)(gbase) + (voff)[_i]), (LAS unsigned*)(lds + (bufoff) + ldsw + _i * 8192), 16, 0, 0); } while (0)
; #define PG8_WAIT_V(n) asm volatile("s_waitcnt vmcnt(" #n ")" ::: "memory")
; #define PG8_BAR __builtin_amdgcn_s_barrier()
; template <class Epi, bool HALFM = false>
; DI void gemm_phase(LAS unsigned char* lds, const Gemm g, const StaticOrder& S, const Epi& E) {
;     ...
;     const char* cA = (const char*)g.A + (size_t)cur.pm * tstepA; const char* cB = (const char*)g.Bt + (size_t)cur.pn * tstepB;
;     PG8_STAGE(PG8_SB(0, 0), cB, voffB); PG8_STAGE(PG8_SB(0, 1), cB + hstepB, voffB); PG8_STAGE(PG8_SA(0, 0), cA, voffA); PG8_STAGE(PG8_SA(0, 1), cA + hstepA, voffA);
;     if (wr == 1) PG8_BAR;
;     PG8_WAIT_V(2); PG8_BAR;
;     PG8_STAGE(PG8_SB(1, 0), cB + kstep, voffB); PG8_STAGE(PG8_SA(1, 0), cA + kstep, voffA); PG8_STAGE(PG8_SB(1, 1), cB + hstepB + kstep, voffB);
;     PG8_WAIT_V(6); PG8_BAR;
;     DI void operator()(const f32x4 (&acc)[2][2][4][2], const Unit& u, int wr, int wc, int fr, int fq) const {
;         const int row0 = u.pm * BM + wr * 64 + fr, col0 = u.pn * 128 + wc * 32 + 8 * fq;
;         float ssv[2][4];
; #pragma unroll
;         for (int ai = 0; ai < 2; ++ai)
; #pragma unroll
;             for (int m = 0; m < 4; ++m) ssv[ai][m] = ss[row0 + ai * HALF + m * 16];
.LBB0_599:
	v_readlane_b32 s8, v254, 34
	v_readlane_b32 s5, v254, 49
	v_readlane_b32 s9, v254, 35
	s_add_u32 s5, s5, s8
	v_readlane_b32 s8, v254, 50
	s_addc_u32 s10, s8, s9
	v_readlane_b32 s8, v254, 13
	v_readlane_b32 s12, v254, 61
	v_readlane_b32 s13, v254, 62
	s_add_u32 s12, s12, s8
	v_readlane_b32 s8, v254, 36
	s_addc_u32 s11, s13, 0
	v_readlane_b32 s9, v254, 37
	s_and_b64 s[8:9], s[8:9], exec
	s_cselect_b32 s11, s10, s11
	s_cselect_b32 s10, s5, s12
	s_lshl_b32 s1, s1, 5
	s_and_b32 s40, s1, 0x60
	s_add_i32 m0, s35, 0x18000
	v_lshl_add_u64 v[8:9], v[8:9], 0, s[2:3]
	s_lshl_b32 s39, s4, 6
	s_lshl_b32 s8, s4, 13
	s_lshl_b32 s1, s40, 7
	global_load_lds_dwordx4 v[8:9], off
	v_lshl_add_u64 v[6:7], v[6:7], 0, s[2:3]
	s_add_i32 m0, s35, 0x1a000
	s_add_i32 s41, s35, 0x8000
	s_add_i32 s42, s35, 0xa000
	global_load_lds_dwordx4 v[6:7], off
	v_lshl_add_u64 v[2:3], v[2:3], 0, s[2:3]
	s_mov_b32 m0, s41
	s_add_u32 s4, s26, 0x40080
	global_load_lds_dwordx4 v[2:3], off
	v_lshl_add_u64 v[2:3], v[4:5], 0, s[2:3]
	s_mov_b32 m0, s42
	s_addc_u32 s5, s27, 0
	global_load_lds_dwordx4 v[2:3], off
	s_add_i32 m0, s35, 0x1c000
	v_lshl_add_u64 v[2:3], s[4:5], 0, v[0:1]
	global_load_lds_dwordx4 v[2:3], off
	v_lshl_add_u64 v[2:3], s[4:5], 0, v[130:131]
	s_add_i32 m0, s35, 0x1e000
	s_movk_i32 s4, 0x3c0
	global_load_lds_dwordx4 v[2:3], off
	s_waitcnt vmcnt(8)
	s_barrier
	v_and_b32_e32 v2, 48, v10
	v_lshlrev_b32_e32 v3, 6, v10
	v_and_or_b32 v2, v3, s4, v2
	v_lshlrev_b32_e32 v3, 2, v10
	v_and_b32_e32 v3, 32, v3
	v_bitop3_b32 v4, v2, s8, v3 bitop3:0xde
	v_bitop3_b32 v144, s1, v2, v3 bitop3:0xf6
	v_lshlrev_b32_e32 v2, 14, v15
	v_and_b32_e32 v2, 0xffff8000, v2
	v_lshl_add_u32 v2, v14, 11, v2
	v_and_b32_e32 v3, 1, v15
	v_lshl_or_b32 v2, v3, 6, v2
	v_lshl_add_u32 v136, v16, 1, v2
	v_lshlrev_b32_e32 v2, 14, v11
	v_and_b32_e32 v2, 0xffff8000, v2
	s_waitcnt vmcnt(6)
	v_lshl_add_u32 v2, v12, 11, v2
	v_and_b32_e32 v3, 1, v11
	s_cmpk_lt_u32 s0, 0x100
	v_lshl_or_b32 v2, v3, 6, v2
	v_readlane_b32 s4, v253, 31
	s_cselect_b64 s[12:13], -1, 0
	v_mov_b32_e32 v137, v1
	v_lshl_add_u32 v138, v13, 1, v2
	v_mov_b32_e32 v139, v1
	s_mov_b32 s43, 0
	v_add_u32_e32 v145, 0x100, v4
	v_readlane_b32 s0, v253, 30
	s_mov_b32 s1, s4
	s_barrier
	v_readlane_b32 s5, v253, 32
	s_lshl_b32 s98, s1, 8
	s_add_i32 s98, s98, s39
	v_and_or_b32 v222, v202, 15, s98
	v_ashrrev_i32_e32 v223, 31, v222
	v_lshl_add_u64 v[222:223], v[222:223], 2, s[10:11]
	global_load_dword v224, v[222:223], off
	global_load_dword v225, v[222:223], off offset:64
	global_load_dword v226, v[222:223], off offset:128
	global_load_dword v227, v[222:223], off offset:192
	global_load_dword v228, v[222:223], off offset:512
	global_load_dword v229, v[222:223], off offset:576
	global_load_dword v230, v[222:223], off offset:640
	global_load_dword v231, v[222:223], off offset:704
	s_branch .LBB0_602

; DI unsigned pk2(float lo, float hi) { f32x2_t v = {lo, hi}; bf16x2_t b = __builtin_convertvector(v, bf16x2_t); return __builtin_bit_cast(unsigned, b); }
; DI float sigmoidf_(float x) { return __builtin_amdgcn_rcpf(1.0f + __builtin_amdgcn_exp2f(x * -1.4426950408889634f)); }
;     DI void operator()(const f32x4 (&acc)[2][2][4][2], const Unit& u, int wr, int wc, int fr, int fq) const {
;         const int row0 = u.pm * BM + wr * 64 + fr, col0 = u.pn * 128 + wc * 32 + 8 * fq;
;         float ssv[2][4];
; #pragma unroll
;         for (int ai = 0; ai < 2; ++ai)
; #pragma unroll
;             for (int m = 0; m < 4; ++m) ssv[ai][m] = ss[row0 + ai * HALF + m * 16];
; #pragma unroll
;         for (int ai = 0; ai < 2; ++ai)
; #pragma unroll
;             for (int m = 0; m < 4; ++m) {
;                 const int r = row0 + ai * HALF + m * 16;
;                 const float rs = __builtin_amdgcn_rsqf(ssv[ai][m] * (1.0f / 1024.0f) + EPS);
;                 float o[8];
; #pragma unroll
;                 for (int n = 0; n < 2; ++n)
; #pragma unroll
;                     for (int e = 0; e < 4; ++e) { const float gg = acc[ai][0][m][n][e] * rs, uu = acc[ai][1][m][n][e] * rs; o[4 * n + e] = gg * sigmoidf_(gg) * uu; }
;                 u32x4 w; w.x = pk2(o[0], o[1]); w.y = pk2(o[2], o[3]); w.z = pk2(o[4], o[5]); w.w = pk2(o[6], o[7]);
;                 *(u32x4*)(O + (size_t)r * ldc + col0) = w;
.LBB0_608:
	s_lshl_b32 s1, s1, 8
	v_mov_b32_e32 v141, v202
	s_add_i32 s1, s1, s39
	s_lshl_b32 s0, s0, 7
	v_and_or_b32 v140, v141, 15, s1
	v_lshrrev_b32_e32 v158, 1, v141
	v_ashrrev_i32_e32 v141, 31, v140
	v_lshl_add_u64 v[142:143], v[140:141], 2, s[10:11]
	v_mov_b32_e32 v159, v224
	v_mov_b32_e32 v162, v225
	v_mov_b32_e32 v156, v226
	v_mov_b32_e32 v154, v227
	v_mov_b32_e32 v152, v228
	v_mov_b32_e32 v150, v229
	v_mov_b32_e32 v148, v230
	v_mov_b32_e32 v146, v231
	v_and_or_b32 v142, v158, 24, s0
	v_readlane_b32 s0, v254, 51
	v_or_b32_e32 v142, s40, v142
	v_readlane_b32 s1, v254, 52
	v_ashrrev_i32_e32 v143, 31, v142
	s_movk_i32 s4, 0x1600
	v_or_b32_e32 v157, 16, v140
	v_or_b32_e32 v155, 32, v140
	v_or_b32_e32 v153, 48, v140
	v_add_u32_e32 v151, 0x80, v140
	v_add_u32_e32 v149, 0x90, v140
	v_add_u32_e32 v147, 0xa0, v140
	v_add_u32_e32 v141, 0xb0, v140
	s_mov_b64 s[24:25], -1
	s_andn2_b64 vcc, exec, s[8:9]
	s_cmp_eq_u64 s[8:9], 0
	s_cbranch_scc1 .Lssn_skip
	s_lshl_b32 s98, s16, 8
	s_add_i32 s98, s98, s39
	v_and_or_b32 v222, v202, 15, s98
	v_ashrrev_i32_e32 v223, 31, v222
	v_lshl_add_u64 v[222:223], v[222:223], 2, s[10:11]
	global_load_dword v224, v[222:223], off
	global_load_dword v225, v[222:223], off offset:64
	global_load_dword v226, v[222:223], off offset:128
	global_load_dword v227, v[222:223], off offset:192
	global_load_dword v228, v[222:223], off offset:512
	global_load_dword v229, v[222:223], off offset:576
	global_load_dword v230, v[222:223], off offset:640
	global_load_dword v231, v[222:223], off offset:704
.Lssn_skip:
	v_fmamk_f32 v158, v159, 0x3a800000, v252
	v_rsq_f32_e32 v158, v158
	s_nop 0
	v_pk_mul_f32 v[126:127], v[126:127], v[158:159] op_sel_hi:[1,0]
	s_nop 0
	v_mul_f32_e32 v159, 0xbfb8aa3b, v126
	v_exp_f32_e32 v159, v159
	s_nop 0
	v_add_f32_e32 v159, 1.0, v159
	v_rcp_f32_e32 v160, v159
	v_pk_mul_f32 v[118:119], v[118:119], v[158:159] op_sel_hi:[1,0]
	v_mul_f32_e32 v159, 0xbfb8aa3b, v127
	v_exp_f32_e32 v159, v159
	s_nop 0
	v_add_f32_e32 v159, 1.0, v159
	v_rcp_f32_e32 v161, v159
	v_pk_mul_f32 v[120:121], v[120:121], v[158:159] op_sel_hi:[1,0]
	v_pk_mul_f32 v[122:123], v[122:123], v[158:159] op_sel_hi:[1,0]
	v_pk_mul_f32 v[114:115], v[114:115], v[158:159] op_sel_hi:[1,0]
	v_pk_mul_f32 v[126:127], v[126:127], v[160:161]
	v_pk_mul_f32 v[116:117], v[116:117], v[158:159] op_sel_hi:[1,0]
	v_pk_mul_f32 v[118:119], v[118:119], v[126:127]
	v_pk_mul_f32 v[126:127], v[128:129], v[158:159] op_sel_hi:[1,0]
	s_nop 0
	v_mul_f32_e32 v128, 0xbfb8aa3b, v126
	v_mul_f32_e32 v129, 0xbfb8aa3b, v127
	v_exp_f32_e32 v128, v128
	v_exp_f32_e32 v129, v129
	v_add_f32_e32 v128, 1.0, v128
	v_add_f32_e32 v129, 1.0, v129
	v_rcp_f32_e32 v128, v128
	v_rcp_f32_e32 v129, v129
	s_nop 0
	v_pk_mul_f32 v[126:127], v[126:127], v[128:129]
	s_nop 0
	v_pk_mul_f32 v[120:121], v[120:121], v[126:127]
	v_mul_f32_e32 v126, 0xbfb8aa3b, v122
	v_mul_f32_e32 v127, 0xbfb8aa3b, v123
	v_exp_f32_e32 v126, v126
	v_exp_f32_e32 v127, v127
	v_add_f32_e32 v126, 1.0, v126
	v_add_f32_e32 v127, 1.0, v127
	v_rcp_f32_e32 v126, v126
	v_rcp_f32_e32 v127, v127
	s_nop 0
	v_pk_mul_f32 v[122:123], v[122:123], v[126:127]
	s_nop 0
	v_pk_mul_f32 v[122:123], v[114:115], v[122:123]
	v_pk_mul_f32 v[114:115], v[124:125], v[158:159] op_sel_hi:[1,0]
	s_nop 0
	v_mul_f32_e32 v124, 0xbfb8aa3b, v114
	v_mul_f32_e32 v125, 0xbfb8aa3b, v115
	v_exp_f32_e32 v124, v124
	v_exp_f32_e32 v125, v125
	v_add_f32_e32 v124, 1.0, v124
	v_add_f32_e32 v125, 1.0, v125
	v_rcp_f32_e32 v124, v124
	v_rcp_f32_e32 v125, v125
	s_nop 0
	v_pk_mul_f32 v[114:115], v[114:115], v[124:125]
	s_nop 0
	v_pk_mul_f32 v[124:125], v[116:117], v[114:115]
	v_cvt_pk_bf16_f32 v114, v118, v119
	v_mov_b64_e32 v[118:119], s[0:1]
	v_cvt_pk_bf16_f32 v115, v120, v121
	v_cvt_pk_bf16_f32 v116, v122, v123
	v_mad_i64_i32 v[122:123], s[0:1], v140, s4, v[118:119]
	v_lshlrev_b64 v[120:121], 1, v[142:143]
	v_cvt_pk_bf16_f32 v117, v124, v125
	v_lshl_add_u64 v[122:123], v[122:123], 0, v[120:121]
	global_store_dwordx4 v[122:123], v[114:117], off
	s_nop 1
	v_fmamk_f32 v114, v162, 0x3a800000, v252
	v_rsq_f32_e32 v114, v114
	s_nop 0
	v_pk_mul_f32 v[110:111], v[110:111], v[114:115] op_sel_hi:[1,0]
	s_nop 0
	v_mul_f32_e32 v115, 0xbfb8aa3b, v110
	v_exp_f32_e32 v115, v115
	s_nop 0
	v_add_f32_e32 v115, 1.0, v115
	v_rcp_f32_e32 v116, v115
	v_pk_mul_f32 v[106:107], v[106:107], v[114:115] op_sel_hi:[1,0]
	v_mul_f32_e32 v115, 0xbfb8aa3b, v111
	v_exp_f32_e32 v115, v115
	s_nop 0
	v_add_f32_e32 v115, 1.0, v115
	v_rcp_f32_e32 v117, v115
	v_pk_mul_f32 v[108:109], v[108:109], v[114:115] op_sel_hi:[1,0]
	v_pk_mul_f32 v[102:103], v[102:103], v[114:115] op_sel_hi:[1,0]
	v_pk_mul_f32 v[98:99], v[98:99], v[114:115] op_sel_hi:[1,0]
	v_pk_mul_f32 v[110:111], v[110:111], v[116:117]
	v_pk_mul_f32 v[100:101], v[100:101], v[114:115] op_sel_hi:[1,0]
	v_pk_mul_f32 v[106:107], v[106:107], v[110:111]
	v_pk_mul_f32 v[110:111], v[112:113], v[114:115] op_sel_hi:[1,0]
	s_nop 0
	v_mul_f32_e32 v112, 0xbfb8aa3b, v110
	v_mul_f32_e32 v113, 0xbfb8aa3b, v111
	v_exp_f32_e32 v112, v112
	v_exp_f32_e32 v113, v113
	v_add_f32_e32 v112, 1.0, v112
	v_add_f32_e32 v113, 1.0, v113
	v_rcp_f32_e32 v112, v112
	v_rcp_f32_e32 v113, v113
	s_nop 0
	v_pk_mul_f32 v[110:111], v[110:111], v[112:113]
	s_nop 0
	v_pk_mul_f32 v[108:109], v[108:109], v[110:111]
	v_mul_f32_e32 v110, 0xbfb8aa3b, v102
	v_mul_f32_e32 v111, 0xbfb8aa3b, v103
	v_exp_f32_e32 v110, v110
	v_exp_f32_e32 v111, v111
	v_add_f32_e32 v110, 1.0, v110
	v_add_f32_e32 v111, 1.0, v111
	v_rcp_f32_e32 v110, v110
	v_rcp_f32_e32 v111, v111
	s_nop 0
	v_pk_mul_f32 v[102:103], v[102:103], v[110:111]
	s_nop 0
	v_pk_mul_f32 v[102:103], v[98:99], v[102:103]
; DI unsigned pk2(float lo, float hi) { f32x2_t v = {lo, hi}; bf16x2_t b = __builtin_convertvector(v, bf16x2_t); return __builtin_bit_cast(unsigned, b); }
; DI float sigmoidf_(float x) { return __builtin_amdgcn_rcpf(1.0f + __builtin_amdgcn_exp2f(x * -1.4426950408889634f)); }
;     DI void operator()(const f32x4 (&acc)[2][2][4][2], const Unit& u, int wr, int wc, int fr, int fq) const {
;     ...
; #pragma unroll
;         for (int ai = 0; ai < 2; ++ai)
; #pragma unroll
;             for (int m = 0; m < 4; ++m) {
;                 const int r = row0 + ai * HALF + m * 16;
;                 const float rs = __builtin_amdgcn_rsqf(ssv[ai][m] * (1.0f / 1024.0f) + EPS);
;                 float o[8];
; #pragma unroll
;                 for (int n = 0; n < 2; ++n)
; #pragma unroll
;                     for (int e = 0; e < 4; ++e) { const float gg = acc[ai][0][m][n][e] * rs, uu = acc[ai][1][m][n][e] * rs; o[4 * n + e] = gg * sigmoidf_(gg) * uu; }
;                 u32x4 w; w.x = pk2(o[0], o[1]); w.y = pk2(o[2], o[3]); w.z = pk2(o[4], o[5]); w.w = pk2(o[6], o[7]);
;                 *(u32x4*)(O + (size_t)r * ldc + col0) = w;
;                 asm volatile("" ::: "memory");
	v_pk_mul_f32 v[98:99], v[104:105], v[114:115] op_sel_hi:[1,0]
	s_nop 0
	v_mul_f32_e32 v104, 0xbfb8aa3b, v98
	v_mul_f32_e32 v105, 0xbfb8aa3b, v99
	v_exp_f32_e32 v104, v104
	v_exp_f32_e32 v105, v105
	v_add_f32_e32 v104, 1.0, v104
	v_add_f32_e32 v105, 1.0, v105
	v_rcp_f32_e32 v104, v104
	v_rcp_f32_e32 v105, v105
	s_nop 0
	v_pk_mul_f32 v[98:99], v[98:99], v[104:105]
	s_nop 0
	v_pk_mul_f32 v[104:105], v[100:101], v[98:99]
	v_cvt_pk_bf16_f32 v100, v102, v103
	v_mad_i64_i32 v[102:103], s[0:1], v157, s4, v[118:119]
	v_cvt_pk_bf16_f32 v98, v106, v107
	v_cvt_pk_bf16_f32 v99, v108, v109
	v_cvt_pk_bf16_f32 v101, v104, v105
	v_lshl_add_u64 v[102:103], v[102:103], 0, v[120:121]
	global_store_dwordx4 v[102:103], v[98:101], off
	s_nop 1
	v_fmamk_f32 v98, v156, 0x3a800000, v252
	v_rsq_f32_e32 v98, v98
	s_nop 0
	v_pk_mul_f32 v[94:95], v[94:95], v[98:99] op_sel_hi:[1,0]
	s_nop 0
	v_mul_f32_e32 v99, 0xbfb8aa3b, v94
	v_exp_f32_e32 v99, v99
	s_nop 0
	v_add_f32_e32 v99, 1.0, v99
	v_rcp_f32_e32 v100, v99
	v_pk_mul_f32 v[90:91], v[90:91], v[98:99] op_sel_hi:[1,0]
	v_mul_f32_e32 v99, 0xbfb8aa3b, v95
	v_exp_f32_e32 v99, v99
	s_nop 0
	v_add_f32_e32 v99, 1.0, v99
	v_rcp_f32_e32 v101, v99
	v_pk_mul_f32 v[92:93], v[92:93], v[98:99] op_sel_hi:[1,0]
	v_pk_mul_f32 v[86:87], v[86:87], v[98:99] op_sel_hi:[1,0]
	v_pk_mul_f32 v[82:83], v[82:83], v[98:99] op_sel_hi:[1,0]
	v_pk_mul_f32 v[94:95], v[94:95], v[100:101]
	v_pk_mul_f32 v[84:85], v[84:85], v[98:99] op_sel_hi:[1,0]
	v_pk_mul_f32 v[90:91], v[90:91], v[94:95]
	v_pk_mul_f32 v[94:95], v[96:97], v[98:99] op_sel_hi:[1,0]
	s_nop 0
	v_mul_f32_e32 v96, 0xbfb8aa3b, v94
	v_mul_f32_e32 v97, 0xbfb8aa3b, v95
	v_exp_f32_e32 v96, v96
	v_exp_f32_e32 v97, v97
	v_add_f32_e32 v96, 1.0, v96
	v_add_f32_e32 v97, 1.0, v97
	v_rcp_f32_e32 v96, v96
	v_rcp_f32_e32 v97, v97
	s_nop 0
	v_pk_mul_f32 v[94:95], v[94:95], v[96:97]
	s_nop 0
	v_pk_mul_f32 v[92:93], v[92:93], v[94:95]
	v_mul_f32_e32 v94, 0xbfb8aa3b, v86
	v_mul_f32_e32 v95, 0xbfb8aa3b, v87
	v_exp_f32_e32 v94, v94
	v_exp_f32_e32 v95, v95
	v_add_f32_e32 v94, 1.0, v94
	v_add_f32_e32 v95, 1.0, v95
	v_rcp_f32_e32 v94, v94
	v_rcp_f32_e32 v95, v95
	s_nop 0
	v_pk_mul_f32 v[86:87], v[86:87], v[94:95]
	s_nop 0
	v_pk_mul_f32 v[86:87], v[82:83], v[86:87]
	v_pk_mul_f32 v[82:83], v[88:89], v[98:99] op_sel_hi:[1,0]
	s_nop 0
	v_mul_f32_e32 v88, 0xbfb8aa3b, v82
	v_mul_f32_e32 v89, 0xbfb8aa3b, v83
	v_exp_f32_e32 v88, v88
	v_exp_f32_e32 v89, v89
	v_add_f32_e32 v88, 1.0, v88
	v_add_f32_e32 v89, 1.0, v89
	v_rcp_f32_e32 v88, v88
	v_rcp_f32_e32 v89, v89
	s_nop 0
	v_pk_mul_f32 v[82:83], v[82:83], v[88:89]
	s_nop 0
	v_pk_mul_f32 v[88:89], v[84:85], v[82:83]
	v_cvt_pk_bf16_f32 v84, v86, v87
	v_mad_i64_i32 v[86:87], s[0:1], v155, s4, v[118:119]
	v_cvt_pk_bf16_f32 v82, v90, v91
	v_cvt_pk_bf16_f32 v83, v92, v93
	v_cvt_pk_bf16_f32 v85, v88, v89
	v_lshl_add_u64 v[86:87], v[86:87], 0, v[120:121]
	global_store_dwordx4 v[86:87], v[82:85], off
	s_nop 1
	v_fmamk_f32 v82, v154, 0x3a800000, v252
	v_rsq_f32_e32 v82, v82
	s_nop 0
	v_pk_mul_f32 v[78:79], v[78:79], v[82:83] op_sel_hi:[1,0]
	s_nop 0
	v_mul_f32_e32 v83, 0xbfb8aa3b, v78
	v_exp_f32_e32 v83, v83
	s_nop 0
	v_add_f32_e32 v83, 1.0, v83
	v_rcp_f32_e32 v84, v83
	v_pk_mul_f32 v[74:75], v[74:75], v[82:83] op_sel_hi:[1,0]
	v_mul_f32_e32 v83, 0xbfb8aa3b, v79
	v_exp_f32_e32 v83, v83
	s_nop 0
	v_add_f32_e32 v83, 1.0, v83
	v_rcp_f32_e32 v85, v83
	v_pk_mul_f32 v[76:77], v[76:77], v[82:83] op_sel_hi:[1,0]
	v_pk_mul_f32 v[70:71], v[70:71], v[82:83] op_sel_hi:[1,0]
	v_pk_mul_f32 v[66:67], v[66:67], v[82:83] op_sel_hi:[1,0]
	v_pk_mul_f32 v[78:79], v[78:79], v[84:85]
	v_pk_mul_f32 v[68:69], v[68:69], v[82:83] op_sel_hi:[1,0]
	v_pk_mul_f32 v[74:75], v[74:75], v[78:79]
	v_pk_mul_f32 v[78:79], v[80:81], v[82:83] op_sel_hi:[1,0]
	s_nop 0
	v_mul_f32_e32 v80, 0xbfb8aa3b, v78
	v_mul_f32_e32 v81, 0xbfb8aa3b, v79
	v_exp_f32_e32 v80, v80
	v_exp_f32_e32 v81, v81
	v_add_f32_e32 v80, 1.0, v80
	v_add_f32_e32 v81, 1.0, v81
	v_rcp_f32_e32 v80, v80
	v_rcp_f32_e32 v81, v81
	s_nop 0
	v_pk_mul_f32 v[78:79], v[78:79], v[80:81]
	s_nop 0
	v_pk_mul_f32 v[76:77], v[76:77], v[78:79]
	v_mul_f32_e32 v78, 0xbfb8aa3b, v70
	v_mul_f32_e32 v79, 0xbfb8aa3b, v71
	v_exp_f32_e32 v78, v78
	v_exp_f32_e32 v79, v79
	v_add_f32_e32 v78, 1.0, v78
	v_add_f32_e32 v79, 1.0, v79
	v_rcp_f32_e32 v78, v78
	v_rcp_f32_e32 v79, v79
	s_nop 0
	v_pk_mul_f32 v[70:71], v[70:71], v[78:79]
	s_nop 0
	v_pk_mul_f32 v[70:71], v[66:67], v[70:71]
	v_pk_mul_f32 v[66:67], v[72:73], v[82:83] op_sel_hi:[1,0]
	s_nop 0
	v_mul_f32_e32 v72, 0xbfb8aa3b, v66
	v_mul_f32_e32 v73, 0xbfb8aa3b, v67
	v_exp_f32_e32 v72, v72
	v_exp_f32_e32 v73, v73
	v_add_f32_e32 v72, 1.0, v72
	v_add_f32_e32 v73, 1.0, v73
	v_rcp_f32_e32 v72, v72
	v_rcp_f32_e32 v73, v73
	s_nop 0
	v_pk_mul_f32 v[66:67], v[66:67], v[72:73]
	s_nop 0
	v_pk_mul_f32 v[72:73], v[68:69], v[66:67]
	v_cvt_pk_bf16_f32 v68, v70, v71
	v_mad_i64_i32 v[70:71], s[0:1], v153, s4, v[118:119]
	v_cvt_pk_bf16_f32 v66, v74, v75
	v_cvt_pk_bf16_f32 v67, v76, v77
	v_cvt_pk_bf16_f32 v69, v72, v73
	v_lshl_add_u64 v[70:71], v[70:71], 0, v[120:121]
	global_store_dwordx4 v[70:71], v[66:69], off
	s_nop 1
	v_fmamk_f32 v66, v152, 0x3a800000, v252
	v_rsq_f32_e32 v66, v66
	s_nop 0
	v_pk_mul_f32 v[62:63], v[62:63], v[66:67] op_sel_hi:[1,0]
	s_nop 0
	v_mul_f32_e32 v67, 0xbfb8aa3b, v62
	v_exp_f32_e32 v67, v67
	s_nop 0
	v_add_f32_e32 v67, 1.0, v67
	v_rcp_f32_e32 v68, v67
	v_pk_mul_f32 v[58:59], v[58:59], v[66:67] op_sel_hi:[1,0]
	v_mul_f32_e32 v67, 0xbfb8aa3b, v63
	v_exp_f32_e32 v67, v67
	s_nop 0
	v_add_f32_e32 v67, 1.0, v67
	v_rcp_f32_e32 v69, v67
	v_pk_mul_f32 v[60:61], v[60:61], v[66:67] op_sel_hi:[1,0]
	v_pk_mul_f32 v[54:55], v[54:55], v[66:67] op_sel_hi:[1,0]
; DI unsigned pk2(float lo, float hi) { f32x2_t v = {lo, hi}; bf16x2_t b = __builtin_convertvector(v, bf16x2_t); return __builtin_bit_cast(unsigned, b); }
; DI float sigmoidf_(float x) { return __builtin_amdgcn_rcpf(1.0f + __builtin_amdgcn_exp2f(x * -1.4426950408889634f)); }
;     DI void operator()(const f32x4 (&acc)[2][2][4][2], const Unit& u, int wr, int wc, int fr, int fq) const {
;     ...
; #pragma unroll
;         for (int ai = 0; ai < 2; ++ai)
; #pragma unroll
;             for (int m = 0; m < 4; ++m) {
;                 const int r = row0 + ai * HALF + m * 16;
;                 const float rs = __builtin_amdgcn_rsqf(ssv[ai][m] * (1.0f / 1024.0f) + EPS);
;                 float o[8];
; #pragma unroll
;                 for (int n = 0; n < 2; ++n)
; #pragma unroll
;                     for (int e = 0; e < 4; ++e) { const float gg = acc[ai][0][m][n][e] * rs, uu = acc[ai][1][m][n][e] * rs; o[4 * n + e] = gg * sigmoidf_(gg) * uu; }
;                 u32x4 w; w.x = pk2(o[0], o[1]); w.y = pk2(o[2], o[3]); w.z = pk2(o[4], o[5]); w.w = pk2(o[6], o[7]);
;                 *(u32x4*)(O + (size_t)r * ldc + col0) = w;
;                 asm volatile("" ::: "memory");
	v_pk_mul_f32 v[50:51], v[50:51], v[66:67] op_sel_hi:[1,0]
	v_pk_mul_f32 v[62:63], v[62:63], v[68:69]
	v_pk_mul_f32 v[52:53], v[52:53], v[66:67] op_sel_hi:[1,0]
	v_pk_mul_f32 v[58:59], v[58:59], v[62:63]
	v_pk_mul_f32 v[62:63], v[64:65], v[66:67] op_sel_hi:[1,0]
	s_nop 0
	v_mul_f32_e32 v64, 0xbfb8aa3b, v62
	v_mul_f32_e32 v65, 0xbfb8aa3b, v63
	v_exp_f32_e32 v64, v64
	v_exp_f32_e32 v65, v65
	v_add_f32_e32 v64, 1.0, v64
	v_add_f32_e32 v65, 1.0, v65
	v_rcp_f32_e32 v64, v64
	v_rcp_f32_e32 v65, v65
	s_nop 0
	v_pk_mul_f32 v[62:63], v[62:63], v[64:65]
	s_nop 0
	v_pk_mul_f32 v[60:61], v[60:61], v[62:63]
	v_mul_f32_e32 v62, 0xbfb8aa3b, v54
	v_mul_f32_e32 v63, 0xbfb8aa3b, v55
	v_exp_f32_e32 v62, v62
	v_exp_f32_e32 v63, v63
	v_add_f32_e32 v62, 1.0, v62
	v_add_f32_e32 v63, 1.0, v63
	v_rcp_f32_e32 v62, v62
	v_rcp_f32_e32 v63, v63
	s_nop 0
	v_pk_mul_f32 v[54:55], v[54:55], v[62:63]
	s_nop 0
	v_pk_mul_f32 v[54:55], v[50:51], v[54:55]
	v_pk_mul_f32 v[50:51], v[56:57], v[66:67] op_sel_hi:[1,0]
	s_nop 0
	v_mul_f32_e32 v56, 0xbfb8aa3b, v50
	v_mul_f32_e32 v57, 0xbfb8aa3b, v51
	v_exp_f32_e32 v56, v56
	v_exp_f32_e32 v57, v57
	v_add_f32_e32 v56, 1.0, v56
	v_add_f32_e32 v57, 1.0, v57
	v_rcp_f32_e32 v56, v56
	v_rcp_f32_e32 v57, v57
	s_nop 0
	v_pk_mul_f32 v[50:51], v[50:51], v[56:57]
	s_nop 0
	v_pk_mul_f32 v[56:57], v[52:53], v[50:51]
	v_cvt_pk_bf16_f32 v52, v54, v55
	v_mad_i64_i32 v[54:55], s[0:1], v151, s4, v[118:119]
	v_cvt_pk_bf16_f32 v50, v58, v59
	v_cvt_pk_bf16_f32 v51, v60, v61
	v_cvt_pk_bf16_f32 v53, v56, v57
	v_lshl_add_u64 v[54:55], v[54:55], 0, v[120:121]
	global_store_dwordx4 v[54:55], v[50:53], off
	s_nop 1
	v_fmamk_f32 v50, v150, 0x3a800000, v252
	v_rsq_f32_e32 v50, v50
	s_nop 0
	v_pk_mul_f32 v[46:47], v[46:47], v[50:51] op_sel_hi:[1,0]
	s_nop 0
	v_mul_f32_e32 v51, 0xbfb8aa3b, v46
	v_exp_f32_e32 v51, v51
	s_nop 0
	v_add_f32_e32 v51, 1.0, v51
	v_rcp_f32_e32 v52, v51
	v_pk_mul_f32 v[42:43], v[42:43], v[50:51] op_sel_hi:[1,0]
	v_mul_f32_e32 v51, 0xbfb8aa3b, v47
	v_exp_f32_e32 v51, v51
	s_nop 0
	v_add_f32_e32 v51, 1.0, v51
	v_rcp_f32_e32 v53, v51
	v_pk_mul_f32 v[44:45], v[44:45], v[50:51] op_sel_hi:[1,0]
	v_pk_mul_f32 v[38:39], v[38:39], v[50:51] op_sel_hi:[1,0]
	v_pk_mul_f32 v[34:35], v[34:35], v[50:51] op_sel_hi:[1,0]
	v_pk_mul_f32 v[46:47], v[46:47], v[52:53]
	v_pk_mul_f32 v[36:37], v[36:37], v[50:51] op_sel_hi:[1,0]
	v_pk_mul_f32 v[42:43], v[42:43], v[46:47]
	v_pk_mul_f32 v[46:47], v[48:49], v[50:51] op_sel_hi:[1,0]
	s_nop 0
	v_mul_f32_e32 v48, 0xbfb8aa3b, v46
	v_mul_f32_e32 v49, 0xbfb8aa3b, v47
	v_exp_f32_e32 v48, v48
	v_exp_f32_e32 v49, v49
	v_add_f32_e32 v48, 1.0, v48
	v_add_f32_e32 v49, 1.0, v49
	v_rcp_f32_e32 v48, v48
	v_rcp_f32_e32 v49, v49
	s_nop 0
	v_pk_mul_f32 v[46:47], v[46:47], v[48:49]
	s_nop 0
	v_pk_mul_f32 v[44:45], v[44:45], v[46:47]
	v_mul_f32_e32 v46, 0xbfb8aa3b, v38
	v_mul_f32_e32 v47, 0xbfb8aa3b, v39
	v_exp_f32_e32 v46, v46
	v_exp_f32_e32 v47, v47
	v_add_f32_e32 v46, 1.0, v46
	v_add_f32_e32 v47, 1.0, v47
	v_rcp_f32_e32 v46, v46
	v_rcp_f32_e32 v47, v47
	s_nop 0
	v_pk_mul_f32 v[38:39], v[38:39], v[46:47]
	s_nop 0
	v_pk_mul_f32 v[38:39], v[34:35], v[38:39]
	v_pk_mul_f32 v[34:35], v[40:41], v[50:51] op_sel_hi:[1,0]
	s_nop 0
	v_mul_f32_e32 v40, 0xbfb8aa3b, v34
	v_mul_f32_e32 v41, 0xbfb8aa3b, v35
	v_exp_f32_e32 v40, v40
	v_exp_f32_e32 v41, v41
	v_add_f32_e32 v40, 1.0, v40
	v_add_f32_e32 v41, 1.0, v41
	v_rcp_f32_e32 v40, v40
	v_rcp_f32_e32 v41, v41
	s_nop 0
	v_pk_mul_f32 v[34:35], v[34:35], v[40:41]
	s_nop 0
	v_pk_mul_f32 v[40:41], v[36:37], v[34:35]
	v_cvt_pk_bf16_f32 v36, v38, v39
	v_mad_i64_i32 v[38:39], s[0:1], v149, s4, v[118:119]
	v_cvt_pk_bf16_f32 v34, v42, v43
	v_cvt_pk_bf16_f32 v35, v44, v45
	v_cvt_pk_bf16_f32 v37, v40, v41
	v_lshl_add_u64 v[38:39], v[38:39], 0, v[120:121]
	global_store_dwordx4 v[38:39], v[34:37], off
	s_nop 1
	v_fmamk_f32 v34, v148, 0x3a800000, v252
	v_rsq_f32_e32 v34, v34
	s_nop 0
	v_pk_mul_f32 v[30:31], v[30:31], v[34:35] op_sel_hi:[1,0]
	s_nop 0
	v_mul_f32_e32 v35, 0xbfb8aa3b, v30
	v_exp_f32_e32 v35, v35
	s_nop 0
	v_add_f32_e32 v35, 1.0, v35
	v_rcp_f32_e32 v36, v35
	v_pk_mul_f32 v[26:27], v[26:27], v[34:35] op_sel_hi:[1,0]
; DI unsigned pk2(float lo, float hi) { f32x2_t v = {lo, hi}; bf16x2_t b = __builtin_convertvector(v, bf16x2_t); return __builtin_bit_cast(unsigned, b); }
; DI float sigmoidf_(float x) { return __builtin_amdgcn_rcpf(1.0f + __builtin_amdgcn_exp2f(x * -1.4426950408889634f)); }
; #define PG8_BAR __builtin_amdgcn_s_barrier()
; template <class Epi, bool HALFM = false>
; DI void gemm_phase(LAS unsigned char* lds, const Gemm g, const StaticOrder& S, const Epi& E) {
;     ...
;         if (!has_next) break;
; #pragma unroll
;         for (int a = 0; a < (HALFM ? 1 : 2); ++a)
; #pragma unroll
;             for (int b = 0; b < 2; ++b)
; #pragma unroll
;                 for (int m = 0; m < 4; ++m)
; #pragma unroll
;                     for (int n = 0; n < 2; ++n) acc[a][b][m][n] = (f32x4){0.f, 0.f, 0.f, 0.f};
;         cur = nxt; cA = nA; cB = nB; ++ui;
;         if (wr == 1) PG8_BAR;
;     DI void operator()(const f32x4 (&acc)[2][2][4][2], const Unit& u, int wr, int wc, int fr, int fq) const {
;     ...
;         for (int ai = 0; ai < 2; ++ai)
; #pragma unroll
;             for (int m = 0; m < 4; ++m) {
;                 const int r = row0 + ai * HALF + m * 16;
;                 const float rs = __builtin_amdgcn_rsqf(ssv[ai][m] * (1.0f / 1024.0f) + EPS);
;                 float o[8];
; #pragma unroll
;                 for (int n = 0; n < 2; ++n)
; #pragma unroll
;                     for (int e = 0; e < 4; ++e) { const float gg = acc[ai][0][m][n][e] * rs, uu = acc[ai][1][m][n][e] * rs; o[4 * n + e] = gg * sigmoidf_(gg) * uu; }
;                 u32x4 w; w.x = pk2(o[0], o[1]); w.y = pk2(o[2], o[3]); w.z = pk2(o[4], o[5]); w.w = pk2(o[6], o[7]);
;                 *(u32x4*)(O + (size_t)r * ldc + col0) = w;
;                 asm volatile("" ::: "memory");
	v_mul_f32_e32 v35, 0xbfb8aa3b, v31
	v_exp_f32_e32 v35, v35
	s_nop 0
	v_add_f32_e32 v35, 1.0, v35
	v_rcp_f32_e32 v37, v35
	v_pk_mul_f32 v[28:29], v[28:29], v[34:35] op_sel_hi:[1,0]
	v_pk_mul_f32 v[22:23], v[22:23], v[34:35] op_sel_hi:[1,0]
	v_pk_mul_f32 v[18:19], v[18:19], v[34:35] op_sel_hi:[1,0]
	v_pk_mul_f32 v[30:31], v[30:31], v[36:37]
	v_pk_mul_f32 v[20:21], v[20:21], v[34:35] op_sel_hi:[1,0]
	v_pk_mul_f32 v[26:27], v[26:27], v[30:31]
	v_pk_mul_f32 v[30:31], v[32:33], v[34:35] op_sel_hi:[1,0]
	s_nop 0
	v_mul_f32_e32 v32, 0xbfb8aa3b, v30
	v_mul_f32_e32 v33, 0xbfb8aa3b, v31
	v_exp_f32_e32 v32, v32
	v_exp_f32_e32 v33, v33
	v_add_f32_e32 v32, 1.0, v32
	v_add_f32_e32 v33, 1.0, v33
	v_rcp_f32_e32 v32, v32
	v_rcp_f32_e32 v33, v33
	s_nop 0
	v_pk_mul_f32 v[30:31], v[30:31], v[32:33]
	s_nop 0
	v_pk_mul_f32 v[28:29], v[28:29], v[30:31]
	v_mul_f32_e32 v30, 0xbfb8aa3b, v22
	v_mul_f32_e32 v31, 0xbfb8aa3b, v23
	v_exp_f32_e32 v30, v30
	v_exp_f32_e32 v31, v31
	v_add_f32_e32 v30, 1.0, v30
	v_add_f32_e32 v31, 1.0, v31
	v_rcp_f32_e32 v30, v30
	v_rcp_f32_e32 v31, v31
	s_nop 0
	v_pk_mul_f32 v[22:23], v[22:23], v[30:31]
	s_nop 0
	v_pk_mul_f32 v[22:23], v[18:19], v[22:23]
	v_pk_mul_f32 v[18:19], v[24:25], v[34:35] op_sel_hi:[1,0]
	s_nop 0
	v_mul_f32_e32 v24, 0xbfb8aa3b, v18
	v_mul_f32_e32 v25, 0xbfb8aa3b, v19
	v_exp_f32_e32 v24, v24
	v_exp_f32_e32 v25, v25
	v_add_f32_e32 v24, 1.0, v24
	v_add_f32_e32 v25, 1.0, v25
	v_rcp_f32_e32 v24, v24
	v_rcp_f32_e32 v25, v25
	s_nop 0
	v_pk_mul_f32 v[18:19], v[18:19], v[24:25]
	s_nop 0
	v_pk_mul_f32 v[24:25], v[20:21], v[18:19]
	v_cvt_pk_bf16_f32 v20, v22, v23
	v_mad_i64_i32 v[22:23], s[0:1], v147, s4, v[118:119]
	v_cvt_pk_bf16_f32 v18, v26, v27
	v_cvt_pk_bf16_f32 v19, v28, v29
	v_cvt_pk_bf16_f32 v21, v24, v25
	v_lshl_add_u64 v[22:23], v[22:23], 0, v[120:121]
	global_store_dwordx4 v[22:23], v[18:21], off
	s_nop 1
	v_fmamk_f32 v18, v146, 0x3a800000, v252
	v_rsq_f32_e32 v18, v18
	s_nop 0
	v_pk_mul_f32 v[14:15], v[14:15], v[18:19] op_sel_hi:[1,0]
	s_nop 0
	v_mul_f32_e32 v19, 0xbfb8aa3b, v14
	v_exp_f32_e32 v19, v19
	s_nop 0
	v_add_f32_e32 v19, 1.0, v19
	v_rcp_f32_e32 v20, v19
	v_pk_mul_f32 v[10:11], v[10:11], v[18:19] op_sel_hi:[1,0]
	v_mul_f32_e32 v19, 0xbfb8aa3b, v15
	v_exp_f32_e32 v19, v19
	s_nop 0
	v_add_f32_e32 v19, 1.0, v19
	v_rcp_f32_e32 v21, v19
	v_pk_mul_f32 v[12:13], v[12:13], v[18:19] op_sel_hi:[1,0]
	v_pk_mul_f32 v[6:7], v[6:7], v[18:19] op_sel_hi:[1,0]
	v_pk_mul_f32 v[2:3], v[2:3], v[18:19] op_sel_hi:[1,0]
	v_pk_mul_f32 v[14:15], v[14:15], v[20:21]
	v_pk_mul_f32 v[4:5], v[4:5], v[18:19] op_sel_hi:[1,0]
	v_pk_mul_f32 v[10:11], v[10:11], v[14:15]
	v_pk_mul_f32 v[14:15], v[16:17], v[18:19] op_sel_hi:[1,0]
	s_nop 0
	v_mul_f32_e32 v16, 0xbfb8aa3b, v14
	v_mul_f32_e32 v17, 0xbfb8aa3b, v15
	v_exp_f32_e32 v16, v16
	v_exp_f32_e32 v17, v17
	v_add_f32_e32 v16, 1.0, v16
	v_add_f32_e32 v17, 1.0, v17
	v_rcp_f32_e32 v16, v16
	v_rcp_f32_e32 v17, v17
	s_nop 0
	v_pk_mul_f32 v[14:15], v[14:15], v[16:17]
	s_nop 0
	v_pk_mul_f32 v[12:13], v[12:13], v[14:15]
	v_mul_f32_e32 v14, 0xbfb8aa3b, v6
	v_mul_f32_e32 v15, 0xbfb8aa3b, v7
	v_exp_f32_e32 v14, v14
	v_exp_f32_e32 v15, v15
	v_add_f32_e32 v14, 1.0, v14
	v_add_f32_e32 v15, 1.0, v15
	v_rcp_f32_e32 v14, v14
	v_rcp_f32_e32 v15, v15
	s_nop 0
	v_pk_mul_f32 v[6:7], v[6:7], v[14:15]
	s_nop 0
	v_pk_mul_f32 v[6:7], v[2:3], v[6:7]
	v_pk_mul_f32 v[2:3], v[8:9], v[18:19] op_sel_hi:[1,0]
	s_nop 0
	v_mul_f32_e32 v8, 0xbfb8aa3b, v2
	v_mul_f32_e32 v9, 0xbfb8aa3b, v3
	v_exp_f32_e32 v8, v8
	v_exp_f32_e32 v9, v9
	v_add_f32_e32 v8, 1.0, v8
	v_add_f32_e32 v9, 1.0, v9
	v_rcp_f32_e32 v8, v8
	v_rcp_f32_e32 v9, v9
	s_nop 0
	v_pk_mul_f32 v[2:3], v[2:3], v[8:9]
	s_nop 0
	v_pk_mul_f32 v[8:9], v[4:5], v[2:3]
	v_cvt_pk_bf16_f32 v4, v6, v7
	v_mad_i64_i32 v[6:7], s[0:1], v141, s4, v[118:119]
	v_cvt_pk_bf16_f32 v2, v10, v11
	v_cvt_pk_bf16_f32 v3, v12, v13
	v_cvt_pk_bf16_f32 v5, v8, v9
	v_lshl_add_u64 v[6:7], v[6:7], 0, v[120:121]
	global_store_dwordx4 v[6:7], v[2:5], off
	s_cbranch_vccnz .LBB0_601
	s_andn2_b64 vcc, exec, s[6:7]
	s_cbranch_vccnz .LBB0_600
	s_barrier
	s_branch .LBB0_600
